# prologue de-serialisation: first operand ds_reads of each GEMM tile issued at the top of the tile block; P8 epilogue waits only for the n=0 weights first
# speedup vs baseline: 1.0313x; 1.0047x over previous
.LBB0_376:
	v_add_u32_e32 v222, 0x18000, v147
	v_add_u32_e32 v223, 0x1c000, v147
	ds_read_b128 v[152:155], v149
	ds_read_b128 v[156:159], v149 offset:1024
	ds_read_b128 v[160:163], v149 offset:2048
	ds_read_b128 v[168:171], v149 offset:3072
	ds_read_b128 v[172:175], v150
	ds_read_b128 v[176:179], v150 offset:1024
	ds_read_b128 v[180:183], v150 offset:2048
	ds_read_b128 v[184:187], v150 offset:3072
	ds_read_b128 v[188:191], v150 offset:4096
	ds_read_b128 v[192:195], v150 offset:5120
	ds_read_b128 v[196:199], v150 offset:6144
	ds_read_b128 v[200:203], v150 offset:7168
	s_ashr_i32 s17, s16, 31
	v_cmp_lt_i64_e32 vcc, s[20:21], v[140:141]
	s_lshl_b64 s[20:21], s[16:17], 20
	s_add_u32 s20, s35, s20
	s_addc_u32 s21, s36, s21
	s_and_b64 s[22:23], vcc, exec
	s_cselect_b32 s17, s21, s25
	s_cselect_b32 s19, s20, s24
	s_ashr_i32 s15, s14, 31
	s_lshl_b64 s[22:23], s[14:15], 20
	s_add_u32 s22, s37, s22
	s_addc_u32 s23, s38, s23
	s_and_b64 s[28:29], vcc, exec
	s_cselect_b32 s15, s23, s27
	s_cselect_b32 s51, s22, s26
	s_add_u32 s24, s24, 0x80080
	s_addc_u32 s25, s25, 0
	s_add_u32 s52, s26, 0x100
	s_addc_u32 s53, s27, 0
	s_mov_b32 s54, -2
	s_add_u32 s26, s24, 0xfff80080
	s_addc_u32 s27, s25, -1
	s_cmp_eq_u32 s54, 28
	s_cselect_b32 s29, s17, s27
	s_cselect_b32 s28, s19, s26
	s_cselect_b32 s27, s15, s53
	s_cselect_b32 s26, s51, s52
	s_add_i32 m0, s39, 0xc000
	s_nop 0
	global_load_lds_dwordx4 v136, s[24:25]
	s_add_i32 m0, s39, 0xe000
	s_nop 0
	global_load_lds_dwordx4 v138, s[24:25]
	s_waitcnt vmcnt(10)
	s_barrier
	s_waitcnt lgkmcnt(0)
	s_setprio 1
	v_mfma_f32_16x16x32_bf16 v[126:129], v[152:155], v[172:175], 0
	ds_read_b128 v[204:207], v151
	v_mfma_f32_16x16x32_bf16 v[122:125], v[160:163], v[172:175], 0
	v_mfma_f32_16x16x32_bf16 v[118:121], v[152:155], v[180:183], 0
	v_mfma_f32_16x16x32_bf16 v[114:117], v[160:163], v[180:183], 0
	v_mfma_f32_16x16x32_bf16 v[102:105], v[152:155], v[188:191], 0
	ds_read_b128 v[208:211], v151 offset:1024
	v_mfma_f32_16x16x32_bf16 v[98:101], v[160:163], v[188:191], 0
	v_mfma_f32_16x16x32_bf16 v[86:89], v[152:155], v[196:199], 0
	v_mfma_f32_16x16x32_bf16 v[82:85], v[160:163], v[196:199], 0
	v_mfma_f32_16x16x32_bf16 v[126:129], v[156:159], v[176:179], v[126:129]
	ds_read_b128 v[212:215], v151 offset:2048
	v_mfma_f32_16x16x32_bf16 v[122:125], v[168:171], v[176:179], v[122:125]
	v_mfma_f32_16x16x32_bf16 v[118:121], v[156:159], v[184:187], v[118:121]
	v_mfma_f32_16x16x32_bf16 v[114:117], v[168:171], v[184:187], v[114:117]
	v_mfma_f32_16x16x32_bf16 v[102:105], v[156:159], v[192:195], v[102:105]
	ds_read_b128 v[216:219], v151 offset:3072
	v_mfma_f32_16x16x32_bf16 v[98:101], v[168:171], v[192:195], v[98:101]
	v_mfma_f32_16x16x32_bf16 v[86:89], v[156:159], v[200:203], v[86:89]
	v_mfma_f32_16x16x32_bf16 v[82:85], v[168:171], v[200:203], v[82:85]
	s_setprio 0
	s_barrier
	s_add_i32 s55, s47, s34
	s_add_u32 s96, s26, 0x80
	s_addc_u32 s97, s27, 0
	s_mov_b32 m0, s55
	s_nop 0
	global_load_lds_dwordx4 v130, s[26:27]
	s_add_i32 m0, s55, 0x2000
	s_nop 0
	global_load_lds_dwordx4 v132, s[26:27]
	s_waitcnt vmcnt(10)
	s_barrier
	s_waitcnt lgkmcnt(0)
	s_setprio 1
	v_mfma_f32_16x16x32_bf16 v[110:113], v[204:207], v[172:175], 0
	ds_read_b128 v[224:227], v150 offset:16384
	v_mfma_f32_16x16x32_bf16 v[106:109], v[212:215], v[172:175], 0
	v_mfma_f32_16x16x32_bf16 v[94:97], v[204:207], v[180:183], 0
	ds_read_b128 v[228:231], v150 offset:17408
	v_mfma_f32_16x16x32_bf16 v[90:93], v[212:215], v[180:183], 0
	v_mfma_f32_16x16x32_bf16 v[78:81], v[204:207], v[188:191], 0
	ds_read_b128 v[232:235], v150 offset:18432
	v_mfma_f32_16x16x32_bf16 v[74:77], v[212:215], v[188:191], 0
	v_mfma_f32_16x16x32_bf16 v[70:73], v[204:207], v[196:199], 0
	ds_read_b128 v[236:239], v150 offset:19456
	v_mfma_f32_16x16x32_bf16 v[66:69], v[212:215], v[196:199], 0
	v_mfma_f32_16x16x32_bf16 v[110:113], v[208:211], v[176:179], v[110:113]
	ds_read_b128 v[240:243], v150 offset:20480
	v_mfma_f32_16x16x32_bf16 v[106:109], v[216:219], v[176:179], v[106:109]
	v_mfma_f32_16x16x32_bf16 v[94:97], v[208:211], v[184:187], v[94:97]
	ds_read_b128 v[244:247], v150 offset:21504
	v_mfma_f32_16x16x32_bf16 v[90:93], v[216:219], v[184:187], v[90:93]
	v_mfma_f32_16x16x32_bf16 v[78:81], v[208:211], v[192:195], v[78:81]
	ds_read_b128 v[248:251], v150 offset:22528
	v_mfma_f32_16x16x32_bf16 v[74:77], v[216:219], v[192:195], v[74:77]
	v_mfma_f32_16x16x32_bf16 v[70:73], v[208:211], v[200:203], v[70:73]
	ds_read_b128 v[164:167], v150 offset:23552
	v_mfma_f32_16x16x32_bf16 v[66:69], v[216:219], v[200:203], v[66:69]
	s_setprio 0
	s_barrier
	s_mov_b32 m0, s39
	s_add_u32 s94, s28, 0x80
	s_addc_u32 s95, s29, 0
	global_load_lds_dwordx4 v130, s[28:29]
	s_mov_b32 m0, s40
	s_nop 0
	global_load_lds_dwordx4 v132, s[28:29]
	s_waitcnt vmcnt(8)
	s_barrier
	s_waitcnt lgkmcnt(0)
	s_setprio 1
	v_mfma_f32_16x16x32_bf16 v[62:65], v[152:155], v[224:227], 0
	ds_read_b128 v[172:175], v150 offset:32768
	v_mfma_f32_16x16x32_bf16 v[58:61], v[160:163], v[224:227], 0
	v_mfma_f32_16x16x32_bf16 v[54:57], v[152:155], v[232:235], 0
	ds_read_b128 v[176:179], v150 offset:33792
	v_mfma_f32_16x16x32_bf16 v[50:53], v[160:163], v[232:235], 0
	v_mfma_f32_16x16x32_bf16 v[38:41], v[152:155], v[240:243], 0
	ds_read_b128 v[180:183], v150 offset:34816
	v_mfma_f32_16x16x32_bf16 v[34:37], v[160:163], v[240:243], 0
	v_mfma_f32_16x16x32_bf16 v[22:25], v[152:155], v[248:251], 0
	ds_read_b128 v[184:187], v150 offset:35840
	v_mfma_f32_16x16x32_bf16 v[18:21], v[160:163], v[248:251], 0
	v_mfma_f32_16x16x32_bf16 v[62:65], v[156:159], v[228:231], v[62:65]
	ds_read_b128 v[188:191], v150 offset:36864
	v_mfma_f32_16x16x32_bf16 v[58:61], v[168:171], v[228:231], v[58:61]
	v_mfma_f32_16x16x32_bf16 v[54:57], v[156:159], v[236:239], v[54:57]
	ds_read_b128 v[192:195], v150 offset:37888
	v_mfma_f32_16x16x32_bf16 v[50:53], v[168:171], v[236:239], v[50:53]
	v_mfma_f32_16x16x32_bf16 v[38:41], v[156:159], v[244:247], v[38:41]
	ds_read_b128 v[196:199], v150 offset:38912
	v_mfma_f32_16x16x32_bf16 v[34:37], v[168:171], v[244:247], v[34:37]
	v_mfma_f32_16x16x32_bf16 v[22:25], v[156:159], v[164:167], v[22:25]
	ds_read_b128 v[200:203], v150 offset:39936
	v_mfma_f32_16x16x32_bf16 v[18:21], v[168:171], v[164:167], v[18:21]
	s_setprio 0
	s_barrier
	s_add_u32 s56, s26, 0x80000
	s_addc_u32 s57, s27, 0
	s_add_i32 s55, s48, s34
	s_mov_b32 m0, s55
	s_nop 0
	global_load_lds_dwordx4 v130, s[56:57]
	s_add_i32 m0, s55, 0x2000
	s_nop 0
	global_load_lds_dwordx4 v132, s[56:57]
	s_waitcnt vmcnt(10)
	s_barrier
	s_waitcnt lgkmcnt(0)
	s_setprio 1
	v_mfma_f32_16x16x32_bf16 v[46:49], v[204:207], v[224:227], 0
	ds_read_b128 v[152:155], v222
	v_mfma_f32_16x16x32_bf16 v[42:45], v[212:215], v[224:227], 0
	v_mfma_f32_16x16x32_bf16 v[30:33], v[204:207], v[232:235], 0
	v_mfma_f32_16x16x32_bf16 v[26:29], v[212:215], v[232:235], 0
	v_mfma_f32_16x16x32_bf16 v[14:17], v[204:207], v[240:243], 0
	ds_read_b128 v[156:159], v222 offset:1024
	v_mfma_f32_16x16x32_bf16 v[10:13], v[212:215], v[240:243], 0
	v_mfma_f32_16x16x32_bf16 v[6:9], v[204:207], v[248:251], 0
	v_mfma_f32_16x16x32_bf16 v[2:5], v[212:215], v[248:251], 0
	v_mfma_f32_16x16x32_bf16 v[46:49], v[208:211], v[228:231], v[46:49]
	ds_read_b128 v[160:163], v222 offset:2048
	v_mfma_f32_16x16x32_bf16 v[42:45], v[216:219], v[228:231], v[42:45]
	v_mfma_f32_16x16x32_bf16 v[30:33], v[208:211], v[236:239], v[30:33]
	v_mfma_f32_16x16x32_bf16 v[26:29], v[216:219], v[236:239], v[26:29]
	v_mfma_f32_16x16x32_bf16 v[14:17], v[208:211], v[244:247], v[14:17]
	ds_read_b128 v[168:171], v222 offset:3072
	v_mfma_f32_16x16x32_bf16 v[10:13], v[216:219], v[244:247], v[10:13]
	v_mfma_f32_16x16x32_bf16 v[6:9], v[208:211], v[164:167], v[6:9]
	v_mfma_f32_16x16x32_bf16 v[2:5], v[216:219], v[164:167], v[2:5]
	s_setprio 0
	s_barrier
	s_add_i32 s55, 0, 0x18000
	s_add_u32 s28, s28, 0x80000
	s_addc_u32 s29, s29, 0
	s_mov_b32 m0, s41
	s_nop 0
	global_load_lds_dwordx4 v130, s[28:29]
	s_mov_b32 m0, s42
	s_nop 0
	global_load_lds_dwordx4 v132, s[28:29]
	s_waitcnt vmcnt(10)
	s_barrier
	s_waitcnt lgkmcnt(0)
	s_setprio 1
	v_mfma_f32_16x16x32_bf16 v[126:129], v[152:155], v[172:175], v[126:129]
	ds_read_b128 v[204:207], v223
	v_mfma_f32_16x16x32_bf16 v[122:125], v[160:163], v[172:175], v[122:125]
	v_mfma_f32_16x16x32_bf16 v[118:121], v[152:155], v[180:183], v[118:121]
	v_mfma_f32_16x16x32_bf16 v[114:117], v[160:163], v[180:183], v[114:117]
	v_mfma_f32_16x16x32_bf16 v[102:105], v[152:155], v[188:191], v[102:105]
	ds_read_b128 v[208:211], v223 offset:1024
	v_mfma_f32_16x16x32_bf16 v[98:101], v[160:163], v[188:191], v[98:101]
	v_mfma_f32_16x16x32_bf16 v[86:89], v[152:155], v[196:199], v[86:89]
	v_mfma_f32_16x16x32_bf16 v[82:85], v[160:163], v[196:199], v[82:85]
	v_mfma_f32_16x16x32_bf16 v[126:129], v[156:159], v[176:179], v[126:129]
	ds_read_b128 v[212:215], v223 offset:2048
	v_mfma_f32_16x16x32_bf16 v[122:125], v[168:171], v[176:179], v[122:125]
	v_mfma_f32_16x16x32_bf16 v[118:121], v[156:159], v[184:187], v[118:121]
	v_mfma_f32_16x16x32_bf16 v[114:117], v[168:171], v[184:187], v[114:117]
	v_mfma_f32_16x16x32_bf16 v[102:105], v[156:159], v[192:195], v[102:105]
	ds_read_b128 v[216:219], v223 offset:3072
	v_mfma_f32_16x16x32_bf16 v[98:101], v[168:171], v[192:195], v[98:101]
	v_mfma_f32_16x16x32_bf16 v[86:89], v[156:159], v[200:203], v[86:89]
	v_mfma_f32_16x16x32_bf16 v[82:85], v[168:171], v[200:203], v[82:85]
	s_setprio 0
	s_barrier
	s_add_i32 s84, 0, 0x1c000
	s_add_i32 s85, s55, s34
	s_mov_b32 m0, s85
	s_nop 0
	global_load_lds_dwordx4 v130, s[96:97]
	s_add_i32 m0, s85, 0x2000
	s_nop 0
	global_load_lds_dwordx4 v132, s[96:97]
	s_waitcnt vmcnt(10)
	s_barrier
	s_waitcnt lgkmcnt(0)
	s_setprio 1
	v_mfma_f32_16x16x32_bf16 v[110:113], v[204:207], v[172:175], v[110:113]
	ds_read_b128 v[224:227], v150 offset:49152
	v_mfma_f32_16x16x32_bf16 v[106:109], v[212:215], v[172:175], v[106:109]
	v_mfma_f32_16x16x32_bf16 v[94:97], v[204:207], v[180:183], v[94:97]
	ds_read_b128 v[228:231], v150 offset:50176
	v_mfma_f32_16x16x32_bf16 v[90:93], v[212:215], v[180:183], v[90:93]
	v_mfma_f32_16x16x32_bf16 v[78:81], v[204:207], v[188:191], v[78:81]
	ds_read_b128 v[232:235], v150 offset:51200
	v_mfma_f32_16x16x32_bf16 v[74:77], v[212:215], v[188:191], v[74:77]
	v_mfma_f32_16x16x32_bf16 v[70:73], v[204:207], v[196:199], v[70:73]
	ds_read_b128 v[236:239], v150 offset:52224
	v_mfma_f32_16x16x32_bf16 v[66:69], v[212:215], v[196:199], v[66:69]
	v_mfma_f32_16x16x32_bf16 v[110:113], v[208:211], v[176:179], v[110:113]
	ds_read_b128 v[240:243], v150 offset:53248
	v_mfma_f32_16x16x32_bf16 v[106:109], v[216:219], v[176:179], v[106:109]
	v_mfma_f32_16x16x32_bf16 v[94:97], v[208:211], v[184:187], v[94:97]
	ds_read_b128 v[244:247], v150 offset:54272
	v_mfma_f32_16x16x32_bf16 v[90:93], v[216:219], v[184:187], v[90:93]
	v_mfma_f32_16x16x32_bf16 v[78:81], v[208:211], v[192:195], v[78:81]
	ds_read_b128 v[248:251], v150 offset:55296
	v_mfma_f32_16x16x32_bf16 v[74:77], v[216:219], v[192:195], v[74:77]
	v_mfma_f32_16x16x32_bf16 v[70:73], v[208:211], v[200:203], v[70:73]
	ds_read_b128 v[164:167], v150 offset:56320
	v_mfma_f32_16x16x32_bf16 v[66:69], v[216:219], v[200:203], v[66:69]
	s_setprio 0
	s_barrier
	s_mov_b32 m0, s45
	s_nop 0
	global_load_lds_dwordx4 v130, s[94:95]
	s_mov_b32 m0, s46
	s_nop 0
	global_load_lds_dwordx4 v132, s[94:95]
	s_waitcnt vmcnt(8)
	s_barrier
	s_waitcnt lgkmcnt(0)
	s_setprio 1
	v_mfma_f32_16x16x32_bf16 v[62:65], v[152:155], v[224:227], v[62:65]
	ds_read_b128 v[172:175], v150
	v_mfma_f32_16x16x32_bf16 v[58:61], v[160:163], v[224:227], v[58:61]
	v_mfma_f32_16x16x32_bf16 v[54:57], v[152:155], v[232:235], v[54:57]
	ds_read_b128 v[176:179], v150 offset:1024
	v_mfma_f32_16x16x32_bf16 v[50:53], v[160:163], v[232:235], v[50:53]
	v_mfma_f32_16x16x32_bf16 v[38:41], v[152:155], v[240:243], v[38:41]
	ds_read_b128 v[180:183], v150 offset:2048
	v_mfma_f32_16x16x32_bf16 v[34:37], v[160:163], v[240:243], v[34:37]
	v_mfma_f32_16x16x32_bf16 v[22:25], v[152:155], v[248:251], v[22:25]
	ds_read_b128 v[184:187], v150 offset:3072
	v_mfma_f32_16x16x32_bf16 v[18:21], v[160:163], v[248:251], v[18:21]
	v_mfma_f32_16x16x32_bf16 v[62:65], v[156:159], v[228:231], v[62:65]
	ds_read_b128 v[188:191], v150 offset:4096
	v_mfma_f32_16x16x32_bf16 v[58:61], v[168:171], v[228:231], v[58:61]
	v_mfma_f32_16x16x32_bf16 v[54:57], v[156:159], v[236:239], v[54:57]
	ds_read_b128 v[192:195], v150 offset:5120
	v_mfma_f32_16x16x32_bf16 v[50:53], v[168:171], v[236:239], v[50:53]
	v_mfma_f32_16x16x32_bf16 v[38:41], v[156:159], v[244:247], v[38:41]
	ds_read_b128 v[196:199], v150 offset:6144
	v_mfma_f32_16x16x32_bf16 v[34:37], v[168:171], v[244:247], v[34:37]
	v_mfma_f32_16x16x32_bf16 v[22:25], v[156:159], v[164:167], v[22:25]
	ds_read_b128 v[200:203], v150 offset:7168
	v_mfma_f32_16x16x32_bf16 v[18:21], v[168:171], v[164:167], v[18:21]
	s_setprio 0
	s_barrier
	s_add_u32 s26, s26, 0x80080
	s_addc_u32 s27, s27, 0
	s_add_i32 s84, s84, s34
	s_mov_b32 m0, s84
	s_nop 0
	global_load_lds_dwordx4 v130, s[26:27]
	s_add_i32 m0, s84, 0x2000
	s_nop 0
	global_load_lds_dwordx4 v132, s[26:27]
	s_waitcnt vmcnt(10)
	s_barrier
	s_waitcnt lgkmcnt(0)
	s_setprio 1
	v_mfma_f32_16x16x32_bf16 v[46:49], v[204:207], v[224:227], v[46:49]
	ds_read_b128 v[152:155], v149
	v_mfma_f32_16x16x32_bf16 v[42:45], v[212:215], v[224:227], v[42:45]
	v_mfma_f32_16x16x32_bf16 v[30:33], v[204:207], v[232:235], v[30:33]
	v_mfma_f32_16x16x32_bf16 v[26:29], v[212:215], v[232:235], v[26:29]
	v_mfma_f32_16x16x32_bf16 v[14:17], v[204:207], v[240:243], v[14:17]
	ds_read_b128 v[156:159], v149 offset:1024
	v_mfma_f32_16x16x32_bf16 v[10:13], v[212:215], v[240:243], v[10:13]
	v_mfma_f32_16x16x32_bf16 v[6:9], v[204:207], v[248:251], v[6:9]
	v_mfma_f32_16x16x32_bf16 v[2:5], v[212:215], v[248:251], v[2:5]
	v_mfma_f32_16x16x32_bf16 v[46:49], v[208:211], v[228:231], v[46:49]
	ds_read_b128 v[160:163], v149 offset:2048
	v_mfma_f32_16x16x32_bf16 v[42:45], v[216:219], v[228:231], v[42:45]
	v_mfma_f32_16x16x32_bf16 v[30:33], v[208:211], v[236:239], v[30:33]
	v_mfma_f32_16x16x32_bf16 v[26:29], v[216:219], v[236:239], v[26:29]
	v_mfma_f32_16x16x32_bf16 v[14:17], v[208:211], v[244:247], v[14:17]
	ds_read_b128 v[168:171], v149 offset:3072
	v_mfma_f32_16x16x32_bf16 v[10:13], v[216:219], v[244:247], v[10:13]
	v_mfma_f32_16x16x32_bf16 v[6:9], v[208:211], v[164:167], v[6:9]
	v_mfma_f32_16x16x32_bf16 v[2:5], v[216:219], v[164:167], v[2:5]
	s_setprio 0
	s_add_i32 s54, s54, 2
	s_add_u32 s24, s24, 0x100
	s_addc_u32 s25, s25, 0
	s_add_u32 s52, s52, 0x100
	s_addc_u32 s53, s53, 0
	s_cmp_gt_u32 s54, 29
	s_barrier
	s_cbranch_scc0 .LBB0_377
	s_branch .Lp2_loop_exit

.LBB0_944:
	v_add_u32_e32 v158, 0x18000, v164
	v_add_u32_e32 v159, 0x1c000, v164
	ds_read_b128 v[130:133], v167
	ds_read_b128 v[134:137], v167 offset:1024
	ds_read_b128 v[138:141], v167 offset:2048
	ds_read_b128 v[142:145], v167 offset:3072
	ds_read_b128 v[172:175], v170
	ds_read_b128 v[176:179], v170 offset:1024
	ds_read_b128 v[180:183], v170 offset:2048
	ds_read_b128 v[184:187], v170 offset:3072
	ds_read_b128 v[188:191], v170 offset:4096
	ds_read_b128 v[192:195], v170 offset:5120
	ds_read_b128 v[196:199], v170 offset:6144
	ds_read_b128 v[200:203], v170 offset:7168
	s_ashr_i32 s29, s28, 31
	v_cmp_lt_i64_e32 vcc, s[30:31], v[154:155]
	s_lshl_b64 s[30:31], s[28:29], 20
	s_add_u32 s30, s48, s30
	s_addc_u32 s31, s49, s31
	s_and_b64 s[34:35], vcc, exec
	s_cselect_b32 s29, s31, s39
	s_cselect_b32 s63, s30, s38
	s_ashr_i32 s27, s26, 31
	s_lshl_b64 s[34:35], s[26:27], 20
	s_add_u32 s34, s54, s34
	s_addc_u32 s35, s55, s35
	s_and_b64 s[42:43], vcc, exec
	s_cselect_b32 s27, s35, s41
	s_cselect_b32 s64, s34, s40
	s_add_u32 s38, s38, 0x80080
	s_addc_u32 s39, s39, 0
	s_add_u32 s65, s40, 0x100
	s_addc_u32 s66, s41, 0
	s_mov_b32 s67, -2
	s_add_u32 s40, s38, 0xfff80080
	s_addc_u32 s41, s39, -1
	s_cmp_eq_u32 s67, 28
	s_cselect_b32 s43, s29, s41
	s_cselect_b32 s42, s63, s40
	s_cselect_b32 s41, s27, s66
	s_cselect_b32 s40, s64, s65
	s_add_i32 m0, s37, 0xc000
	s_nop 0
	global_load_lds_dwordx4 v150, s[38:39]
	s_add_i32 m0, s37, 0xe000
	s_nop 0
	global_load_lds_dwordx4 v152, s[38:39]
	s_waitcnt vmcnt(10)
	s_barrier
	s_waitcnt lgkmcnt(0)
	s_setprio 1
	v_mfma_f32_16x16x32_bf16 v[126:129], v[130:133], v[172:175], 0
	ds_read_b128 v[204:207], v171
	v_mfma_f32_16x16x32_bf16 v[122:125], v[138:141], v[172:175], 0
	v_mfma_f32_16x16x32_bf16 v[114:117], v[130:133], v[180:183], 0
	v_mfma_f32_16x16x32_bf16 v[106:109], v[138:141], v[180:183], 0
	v_mfma_f32_16x16x32_bf16 v[98:101], v[130:133], v[188:191], 0
	ds_read_b128 v[208:211], v171 offset:1024
	v_mfma_f32_16x16x32_bf16 v[90:93], v[138:141], v[188:191], 0
	v_mfma_f32_16x16x32_bf16 v[82:85], v[130:133], v[196:199], 0
	v_mfma_f32_16x16x32_bf16 v[74:77], v[138:141], v[196:199], 0
	v_mfma_f32_16x16x32_bf16 v[126:129], v[134:137], v[176:179], v[126:129]
	ds_read_b128 v[212:215], v171 offset:2048
	v_mfma_f32_16x16x32_bf16 v[122:125], v[142:145], v[176:179], v[122:125]
	v_mfma_f32_16x16x32_bf16 v[114:117], v[134:137], v[184:187], v[114:117]
	v_mfma_f32_16x16x32_bf16 v[106:109], v[142:145], v[184:187], v[106:109]
	v_mfma_f32_16x16x32_bf16 v[98:101], v[134:137], v[192:195], v[98:101]
	ds_read_b128 v[216:219], v171 offset:3072
	v_mfma_f32_16x16x32_bf16 v[90:93], v[142:145], v[192:195], v[90:93]
	v_mfma_f32_16x16x32_bf16 v[82:85], v[134:137], v[200:203], v[82:85]
	v_mfma_f32_16x16x32_bf16 v[74:77], v[142:145], v[200:203], v[74:77]
	s_setprio 0
	s_barrier
	s_add_i32 s68, s59, s47
	s_add_u32 s96, s40, 0x80
	s_addc_u32 s97, s41, 0
	s_mov_b32 m0, s68
	s_nop 0
	global_load_lds_dwordx4 v146, s[40:41]
	s_add_i32 m0, s68, 0x2000
	s_nop 0
	global_load_lds_dwordx4 v148, s[40:41]
	s_waitcnt vmcnt(10)
	s_barrier
	s_waitcnt lgkmcnt(0)
	s_setprio 1
	v_mfma_f32_16x16x32_bf16 v[118:121], v[204:207], v[172:175], 0
	ds_read_b128 v[224:227], v170 offset:16384
	v_mfma_f32_16x16x32_bf16 v[110:113], v[212:215], v[172:175], 0
	v_mfma_f32_16x16x32_bf16 v[102:105], v[204:207], v[180:183], 0
	ds_read_b128 v[228:231], v170 offset:17408
	v_mfma_f32_16x16x32_bf16 v[94:97], v[212:215], v[180:183], 0
	v_mfma_f32_16x16x32_bf16 v[86:89], v[204:207], v[188:191], 0
	ds_read_b128 v[232:235], v170 offset:18432
	v_mfma_f32_16x16x32_bf16 v[78:81], v[212:215], v[188:191], 0
	v_mfma_f32_16x16x32_bf16 v[70:73], v[204:207], v[196:199], 0
	ds_read_b128 v[236:239], v170 offset:19456
	v_mfma_f32_16x16x32_bf16 v[66:69], v[212:215], v[196:199], 0
	v_mfma_f32_16x16x32_bf16 v[118:121], v[208:211], v[176:179], v[118:121]
	ds_read_b128 v[240:243], v170 offset:20480
	v_mfma_f32_16x16x32_bf16 v[110:113], v[216:219], v[176:179], v[110:113]
	v_mfma_f32_16x16x32_bf16 v[102:105], v[208:211], v[184:187], v[102:105]
	ds_read_b128 v[244:247], v170 offset:21504
	v_mfma_f32_16x16x32_bf16 v[94:97], v[216:219], v[184:187], v[94:97]
	v_mfma_f32_16x16x32_bf16 v[86:89], v[208:211], v[192:195], v[86:89]
	ds_read_b128 v[248:251], v170 offset:22528
	v_mfma_f32_16x16x32_bf16 v[78:81], v[216:219], v[192:195], v[78:81]
	v_mfma_f32_16x16x32_bf16 v[70:73], v[208:211], v[200:203], v[70:73]
	ds_read_b128 v[220:223], v170 offset:23552
	v_mfma_f32_16x16x32_bf16 v[66:69], v[216:219], v[200:203], v[66:69]
	s_setprio 0
	s_barrier
	s_mov_b32 m0, s37
	s_add_u32 s94, s42, 0x80
	s_addc_u32 s95, s43, 0
	global_load_lds_dwordx4 v146, s[42:43]
	s_mov_b32 m0, s50
	s_nop 0
	global_load_lds_dwordx4 v148, s[42:43]
	s_waitcnt vmcnt(8)
	s_barrier
	s_waitcnt lgkmcnt(0)
	s_setprio 1
	v_mfma_f32_16x16x32_bf16 v[62:65], v[130:133], v[224:227], 0
	ds_read_b128 v[172:175], v170 offset:32768
	v_mfma_f32_16x16x32_bf16 v[58:61], v[138:141], v[224:227], 0
	v_mfma_f32_16x16x32_bf16 v[54:57], v[130:133], v[232:235], 0
	ds_read_b128 v[176:179], v170 offset:33792
	v_mfma_f32_16x16x32_bf16 v[46:49], v[138:141], v[232:235], 0
	v_mfma_f32_16x16x32_bf16 v[38:41], v[130:133], v[240:243], 0
	ds_read_b128 v[180:183], v170 offset:34816
	v_mfma_f32_16x16x32_bf16 v[30:33], v[138:141], v[240:243], 0
	v_mfma_f32_16x16x32_bf16 v[22:25], v[130:133], v[248:251], 0
	ds_read_b128 v[184:187], v170 offset:35840
	v_mfma_f32_16x16x32_bf16 v[14:17], v[138:141], v[248:251], 0
	v_mfma_f32_16x16x32_bf16 v[62:65], v[134:137], v[228:231], v[62:65]
	ds_read_b128 v[188:191], v170 offset:36864
	v_mfma_f32_16x16x32_bf16 v[58:61], v[142:145], v[228:231], v[58:61]
	v_mfma_f32_16x16x32_bf16 v[54:57], v[134:137], v[236:239], v[54:57]
	ds_read_b128 v[192:195], v170 offset:37888
	v_mfma_f32_16x16x32_bf16 v[46:49], v[142:145], v[236:239], v[46:49]
	v_mfma_f32_16x16x32_bf16 v[38:41], v[134:137], v[244:247], v[38:41]
	ds_read_b128 v[196:199], v170 offset:38912
	v_mfma_f32_16x16x32_bf16 v[30:33], v[142:145], v[244:247], v[30:33]
	v_mfma_f32_16x16x32_bf16 v[22:25], v[134:137], v[220:223], v[22:25]
	ds_read_b128 v[200:203], v170 offset:39936
	v_mfma_f32_16x16x32_bf16 v[14:17], v[142:145], v[220:223], v[14:17]
	s_setprio 0
	s_barrier
	s_add_u32 s68, s40, 0x80000
	s_addc_u32 s69, s41, 0
	s_add_i32 s70, s60, s47
	s_mov_b32 m0, s70
	s_nop 0
	global_load_lds_dwordx4 v146, s[68:69]
	s_add_i32 m0, s70, 0x2000
	s_nop 0
	global_load_lds_dwordx4 v148, s[68:69]
	s_waitcnt vmcnt(10)
	s_barrier
	s_waitcnt lgkmcnt(0)
	s_setprio 1
	v_mfma_f32_16x16x32_bf16 v[50:53], v[204:207], v[224:227], 0
	ds_read_b128 v[130:133], v158
	v_mfma_f32_16x16x32_bf16 v[42:45], v[212:215], v[224:227], 0
	v_mfma_f32_16x16x32_bf16 v[34:37], v[204:207], v[232:235], 0
	v_mfma_f32_16x16x32_bf16 v[26:29], v[212:215], v[232:235], 0
	v_mfma_f32_16x16x32_bf16 v[18:21], v[204:207], v[240:243], 0
	ds_read_b128 v[134:137], v158 offset:1024
	v_mfma_f32_16x16x32_bf16 v[10:13], v[212:215], v[240:243], 0
	v_mfma_f32_16x16x32_bf16 v[6:9], v[204:207], v[248:251], 0
	v_mfma_f32_16x16x32_bf16 v[2:5], v[212:215], v[248:251], 0
	v_mfma_f32_16x16x32_bf16 v[50:53], v[208:211], v[228:231], v[50:53]
	ds_read_b128 v[138:141], v158 offset:2048
	v_mfma_f32_16x16x32_bf16 v[42:45], v[216:219], v[228:231], v[42:45]
	v_mfma_f32_16x16x32_bf16 v[34:37], v[208:211], v[236:239], v[34:37]
	v_mfma_f32_16x16x32_bf16 v[26:29], v[216:219], v[236:239], v[26:29]
	v_mfma_f32_16x16x32_bf16 v[18:21], v[208:211], v[244:247], v[18:21]
	ds_read_b128 v[142:145], v158 offset:3072
	v_mfma_f32_16x16x32_bf16 v[10:13], v[216:219], v[244:247], v[10:13]
	v_mfma_f32_16x16x32_bf16 v[6:9], v[208:211], v[220:223], v[6:9]
	v_mfma_f32_16x16x32_bf16 v[2:5], v[216:219], v[220:223], v[2:5]
	s_setprio 0
	s_barrier
	s_add_i32 s70, 0, 0x18000
	s_add_u32 s42, s42, 0x80000
	s_addc_u32 s43, s43, 0
	s_mov_b32 m0, s51
	s_nop 0
	global_load_lds_dwordx4 v146, s[42:43]
	s_mov_b32 m0, s52
	s_nop 0
	global_load_lds_dwordx4 v148, s[42:43]
	s_waitcnt vmcnt(10)
	s_barrier
	s_waitcnt lgkmcnt(0)
	s_setprio 1
	v_mfma_f32_16x16x32_bf16 v[126:129], v[130:133], v[172:175], v[126:129]
	ds_read_b128 v[204:207], v159
	v_mfma_f32_16x16x32_bf16 v[122:125], v[138:141], v[172:175], v[122:125]
	v_mfma_f32_16x16x32_bf16 v[114:117], v[130:133], v[180:183], v[114:117]
	v_mfma_f32_16x16x32_bf16 v[106:109], v[138:141], v[180:183], v[106:109]
	v_mfma_f32_16x16x32_bf16 v[98:101], v[130:133], v[188:191], v[98:101]
	ds_read_b128 v[208:211], v159 offset:1024
	v_mfma_f32_16x16x32_bf16 v[90:93], v[138:141], v[188:191], v[90:93]
	v_mfma_f32_16x16x32_bf16 v[82:85], v[130:133], v[196:199], v[82:85]
	v_mfma_f32_16x16x32_bf16 v[74:77], v[138:141], v[196:199], v[74:77]
	v_mfma_f32_16x16x32_bf16 v[126:129], v[134:137], v[176:179], v[126:129]
	ds_read_b128 v[212:215], v159 offset:2048
	v_mfma_f32_16x16x32_bf16 v[122:125], v[142:145], v[176:179], v[122:125]
	v_mfma_f32_16x16x32_bf16 v[114:117], v[134:137], v[184:187], v[114:117]
	v_mfma_f32_16x16x32_bf16 v[106:109], v[142:145], v[184:187], v[106:109]
	v_mfma_f32_16x16x32_bf16 v[98:101], v[134:137], v[192:195], v[98:101]
	ds_read_b128 v[216:219], v159 offset:3072
	v_mfma_f32_16x16x32_bf16 v[90:93], v[142:145], v[192:195], v[90:93]
	v_mfma_f32_16x16x32_bf16 v[82:85], v[134:137], v[200:203], v[82:85]
	v_mfma_f32_16x16x32_bf16 v[74:77], v[142:145], v[200:203], v[74:77]
	s_setprio 0
	s_barrier
	s_add_i32 s84, 0, 0x1c000
	s_add_i32 s85, s70, s47
	s_mov_b32 m0, s85
	s_nop 0
	global_load_lds_dwordx4 v146, s[96:97]
	s_add_i32 m0, s85, 0x2000
	s_nop 0
	global_load_lds_dwordx4 v148, s[96:97]
	s_waitcnt vmcnt(10)
	s_barrier
	s_waitcnt lgkmcnt(0)
	s_setprio 1
	v_mfma_f32_16x16x32_bf16 v[118:121], v[204:207], v[172:175], v[118:121]
	ds_read_b128 v[224:227], v170 offset:49152
	v_mfma_f32_16x16x32_bf16 v[110:113], v[212:215], v[172:175], v[110:113]
	v_mfma_f32_16x16x32_bf16 v[102:105], v[204:207], v[180:183], v[102:105]
	ds_read_b128 v[228:231], v170 offset:50176
	v_mfma_f32_16x16x32_bf16 v[94:97], v[212:215], v[180:183], v[94:97]
	v_mfma_f32_16x16x32_bf16 v[86:89], v[204:207], v[188:191], v[86:89]
	ds_read_b128 v[232:235], v170 offset:51200
	v_mfma_f32_16x16x32_bf16 v[78:81], v[212:215], v[188:191], v[78:81]
	v_mfma_f32_16x16x32_bf16 v[70:73], v[204:207], v[196:199], v[70:73]
	ds_read_b128 v[236:239], v170 offset:52224
	v_mfma_f32_16x16x32_bf16 v[66:69], v[212:215], v[196:199], v[66:69]
	v_mfma_f32_16x16x32_bf16 v[118:121], v[208:211], v[176:179], v[118:121]
	ds_read_b128 v[240:243], v170 offset:53248
	v_mfma_f32_16x16x32_bf16 v[110:113], v[216:219], v[176:179], v[110:113]
	v_mfma_f32_16x16x32_bf16 v[102:105], v[208:211], v[184:187], v[102:105]
	ds_read_b128 v[244:247], v170 offset:54272
	v_mfma_f32_16x16x32_bf16 v[94:97], v[216:219], v[184:187], v[94:97]
	v_mfma_f32_16x16x32_bf16 v[86:89], v[208:211], v[192:195], v[86:89]
	ds_read_b128 v[248:251], v170 offset:55296
	v_mfma_f32_16x16x32_bf16 v[78:81], v[216:219], v[192:195], v[78:81]
	v_mfma_f32_16x16x32_bf16 v[70:73], v[208:211], v[200:203], v[70:73]
	ds_read_b128 v[220:223], v170 offset:56320
	v_mfma_f32_16x16x32_bf16 v[66:69], v[216:219], v[200:203], v[66:69]
	s_setprio 0
	s_barrier
	s_mov_b32 m0, s57
	s_nop 0
	global_load_lds_dwordx4 v146, s[94:95]
	s_mov_b32 m0, s58
	s_nop 0
	global_load_lds_dwordx4 v148, s[94:95]
	s_waitcnt vmcnt(8)
	s_barrier
	s_waitcnt lgkmcnt(0)
	s_setprio 1
	v_mfma_f32_16x16x32_bf16 v[62:65], v[130:133], v[224:227], v[62:65]
	ds_read_b128 v[172:175], v170
	v_mfma_f32_16x16x32_bf16 v[58:61], v[138:141], v[224:227], v[58:61]
	v_mfma_f32_16x16x32_bf16 v[54:57], v[130:133], v[232:235], v[54:57]
	ds_read_b128 v[176:179], v170 offset:1024
	v_mfma_f32_16x16x32_bf16 v[46:49], v[138:141], v[232:235], v[46:49]
	v_mfma_f32_16x16x32_bf16 v[38:41], v[130:133], v[240:243], v[38:41]
	ds_read_b128 v[180:183], v170 offset:2048
	v_mfma_f32_16x16x32_bf16 v[30:33], v[138:141], v[240:243], v[30:33]
	v_mfma_f32_16x16x32_bf16 v[22:25], v[130:133], v[248:251], v[22:25]
	ds_read_b128 v[184:187], v170 offset:3072
	v_mfma_f32_16x16x32_bf16 v[14:17], v[138:141], v[248:251], v[14:17]
	v_mfma_f32_16x16x32_bf16 v[62:65], v[134:137], v[228:231], v[62:65]
	ds_read_b128 v[188:191], v170 offset:4096
	v_mfma_f32_16x16x32_bf16 v[58:61], v[142:145], v[228:231], v[58:61]
	v_mfma_f32_16x16x32_bf16 v[54:57], v[134:137], v[236:239], v[54:57]
	ds_read_b128 v[192:195], v170 offset:5120
	v_mfma_f32_16x16x32_bf16 v[46:49], v[142:145], v[236:239], v[46:49]
	v_mfma_f32_16x16x32_bf16 v[38:41], v[134:137], v[244:247], v[38:41]
	ds_read_b128 v[196:199], v170 offset:6144
	v_mfma_f32_16x16x32_bf16 v[30:33], v[142:145], v[244:247], v[30:33]
	v_mfma_f32_16x16x32_bf16 v[22:25], v[134:137], v[220:223], v[22:25]
	ds_read_b128 v[200:203], v170 offset:7168
	v_mfma_f32_16x16x32_bf16 v[14:17], v[142:145], v[220:223], v[14:17]
	s_setprio 0
	s_barrier
	s_add_u32 s40, s40, 0x80080
	s_addc_u32 s41, s41, 0
	s_add_i32 s84, s84, s47
	s_mov_b32 m0, s84
	s_nop 0
	global_load_lds_dwordx4 v146, s[40:41]
	s_add_i32 m0, s84, 0x2000
	s_nop 0
	global_load_lds_dwordx4 v148, s[40:41]
	s_waitcnt vmcnt(10)
	s_barrier
	s_waitcnt lgkmcnt(0)
	s_setprio 1
	v_mfma_f32_16x16x32_bf16 v[50:53], v[204:207], v[224:227], v[50:53]
	ds_read_b128 v[130:133], v167
	v_mfma_f32_16x16x32_bf16 v[42:45], v[212:215], v[224:227], v[42:45]
	v_mfma_f32_16x16x32_bf16 v[34:37], v[204:207], v[232:235], v[34:37]
	v_mfma_f32_16x16x32_bf16 v[26:29], v[212:215], v[232:235], v[26:29]
	v_mfma_f32_16x16x32_bf16 v[18:21], v[204:207], v[240:243], v[18:21]
	ds_read_b128 v[134:137], v167 offset:1024
	v_mfma_f32_16x16x32_bf16 v[10:13], v[212:215], v[240:243], v[10:13]
	v_mfma_f32_16x16x32_bf16 v[6:9], v[204:207], v[248:251], v[6:9]
	v_mfma_f32_16x16x32_bf16 v[2:5], v[212:215], v[248:251], v[2:5]
	v_mfma_f32_16x16x32_bf16 v[50:53], v[208:211], v[228:231], v[50:53]
	ds_read_b128 v[138:141], v167 offset:2048
	v_mfma_f32_16x16x32_bf16 v[42:45], v[216:219], v[228:231], v[42:45]
	v_mfma_f32_16x16x32_bf16 v[34:37], v[208:211], v[236:239], v[34:37]
	v_mfma_f32_16x16x32_bf16 v[26:29], v[216:219], v[236:239], v[26:29]
	v_mfma_f32_16x16x32_bf16 v[18:21], v[208:211], v[244:247], v[18:21]
	ds_read_b128 v[142:145], v167 offset:3072
	v_mfma_f32_16x16x32_bf16 v[10:13], v[216:219], v[244:247], v[10:13]
	v_mfma_f32_16x16x32_bf16 v[6:9], v[208:211], v[220:223], v[6:9]
	v_mfma_f32_16x16x32_bf16 v[2:5], v[216:219], v[220:223], v[2:5]
	s_setprio 0
	s_add_i32 s67, s67, 2
	s_add_u32 s38, s38, 0x100
	s_addc_u32 s39, s39, 0
	s_add_u32 s65, s65, 0x100
	s_addc_u32 s66, s66, 0
	s_cmp_gt_u32 s67, 29
	s_barrier
	s_cbranch_scc0 .LBB0_945
	s_branch .Lp6_loop_exit

.LBB0_1097:
	v_add_u32_e32 v168, 0x18000, v236
	v_add_u32_e32 v169, 0x1c000, v236
	ds_read_b128 v[130:133], v240
	ds_read_b128 v[134:137], v240 offset:1024
	ds_read_b128 v[138:141], v240 offset:2048
	ds_read_b128 v[142:145], v240 offset:3072
	ds_read_b128 v[146:149], v241
	ds_read_b128 v[150:153], v241 offset:1024
	ds_read_b128 v[154:157], v241 offset:2048
	ds_read_b128 v[158:161], v241 offset:3072
	ds_read_b128 v[176:179], v241 offset:4096
	ds_read_b128 v[180:183], v241 offset:5120
	ds_read_b128 v[184:187], v241 offset:6144
	ds_read_b128 v[188:191], v241 offset:7168
	s_ashr_i32 s41, s40, 31
	v_cmp_lt_i64_e32 vcc, s[42:43], v[172:173]
	s_lshl_b64 s[42:43], s[40:41], 20
	s_add_u32 s42, s57, s42
	s_addc_u32 s43, s58, s43
	s_add_u32 s42, s42, s89
	s_addc_u32 s43, s43, 0
	s_and_b64 s[44:45], vcc, exec
	s_cselect_b32 s41, s43, s49
	s_cselect_b32 s47, s42, s48
	s_ashr_i32 s39, s38, 31
	s_lshl_b64 s[44:45], s[38:39], 20
	s_add_u32 s44, s18, s44
	s_addc_u32 s45, s19, s45
	s_add_u32 s44, s44, s89
	s_addc_u32 s45, s45, 0
	s_and_b64 s[52:53], vcc, exec
	s_cselect_b32 s39, s45, s51
	s_cselect_b32 s73, s44, s50
	s_add_u32 s48, s48, 0x80080
	s_addc_u32 s49, s49, 0
	s_add_u32 s74, s50, 0x100
	s_addc_u32 s75, s51, 0
	s_mov_b32 s80, -2
	s_cmpk_gt_u32 s56, 0xfff
	s_cbranch_scc1 .Lp8_nostage
	s_lshr_b32 s84, s56, 10
	s_mul_i32 s85, s84, 0xb000
	s_add_u32 s94, s12, s85
	s_addc_u32 s95, s13, 0
	s_cmp_eq_u32 s84, 3
	s_cselect_b32 s94, s14, s94
	s_cselect_b32 s95, s15, s95
	s_lshl_b32 s85, s46, 9
	s_add_u32 s94, s94, s85
	s_addc_u32 s95, s95, 0
	s_add_i32 m0, s86, s56
	s_nop 0
	global_load_lds_dwordx4 v245, s[94:95]
.Lp8_nostage:
	s_add_u32 s50, s48, 0xfff80080
	s_addc_u32 s51, s49, -1
	s_cmp_eq_u32 s80, s87
	s_cselect_b32 s53, s41, s51
	s_cselect_b32 s52, s47, s50
	s_cselect_b32 s51, s39, s75
	s_cselect_b32 s50, s73, s74
	s_add_i32 m0, s21, 0xc000
	s_nop 0
	global_load_lds_dwordx4 v166, s[48:49]
	s_add_i32 m0, s21, 0xe000
	s_nop 0
	global_load_lds_dwordx4 v170, s[48:49]
	s_waitcnt vmcnt(10)
	s_barrier
	s_waitcnt lgkmcnt(0)
	s_setprio 1
	v_mfma_f32_16x16x32_bf16 v[126:129], v[130:133], v[146:149], 0
	ds_read_b128 v[192:195], v242
	v_mfma_f32_16x16x32_bf16 v[122:125], v[138:141], v[146:149], 0
	v_mfma_f32_16x16x32_bf16 v[118:121], v[130:133], v[154:157], 0
	v_mfma_f32_16x16x32_bf16 v[114:117], v[138:141], v[154:157], 0
	v_mfma_f32_16x16x32_bf16 v[106:109], v[130:133], v[176:179], 0
	ds_read_b128 v[196:199], v242 offset:1024
	v_mfma_f32_16x16x32_bf16 v[98:101], v[138:141], v[176:179], 0
	v_mfma_f32_16x16x32_bf16 v[90:93], v[130:133], v[184:187], 0
	v_mfma_f32_16x16x32_bf16 v[82:85], v[138:141], v[184:187], 0
	v_mfma_f32_16x16x32_bf16 v[126:129], v[134:137], v[150:153], v[126:129]
	ds_read_b128 v[200:203], v242 offset:2048
	v_mfma_f32_16x16x32_bf16 v[122:125], v[142:145], v[150:153], v[122:125]
	v_mfma_f32_16x16x32_bf16 v[118:121], v[134:137], v[158:161], v[118:121]
	v_mfma_f32_16x16x32_bf16 v[114:117], v[142:145], v[158:161], v[114:117]
	v_mfma_f32_16x16x32_bf16 v[106:109], v[134:137], v[180:183], v[106:109]
	ds_read_b128 v[204:207], v242 offset:3072
	v_mfma_f32_16x16x32_bf16 v[98:101], v[142:145], v[180:183], v[98:101]
	v_mfma_f32_16x16x32_bf16 v[90:93], v[134:137], v[188:191], v[90:93]
	v_mfma_f32_16x16x32_bf16 v[82:85], v[142:145], v[188:191], v[82:85]
	s_setprio 0
	s_barrier
	s_add_i32 s81, s68, s56
	s_add_u32 s96, s50, 0x80
	s_addc_u32 s97, s51, 0
	s_mov_b32 m0, s81
	s_nop 0
	global_load_lds_dwordx4 v162, s[50:51]
	s_add_i32 m0, s81, 0x2000
	s_nop 0
	global_load_lds_dwordx4 v164, s[50:51]
	s_waitcnt vmcnt(10)
	s_barrier
	s_waitcnt lgkmcnt(0)
	s_setprio 1
	v_mfma_f32_16x16x32_bf16 v[110:113], v[192:195], v[146:149], 0
	ds_read_b128 v[208:211], v241 offset:16384
	v_mfma_f32_16x16x32_bf16 v[102:105], v[200:203], v[146:149], 0
	v_mfma_f32_16x16x32_bf16 v[94:97], v[192:195], v[154:157], 0
	ds_read_b128 v[212:215], v241 offset:17408
	v_mfma_f32_16x16x32_bf16 v[86:89], v[200:203], v[154:157], 0
	v_mfma_f32_16x16x32_bf16 v[78:81], v[192:195], v[176:179], 0
	ds_read_b128 v[216:219], v241 offset:18432
	v_mfma_f32_16x16x32_bf16 v[74:77], v[200:203], v[176:179], 0
	v_mfma_f32_16x16x32_bf16 v[70:73], v[192:195], v[184:187], 0
	ds_read_b128 v[220:223], v241 offset:19456
	v_mfma_f32_16x16x32_bf16 v[66:69], v[200:203], v[184:187], 0
	v_mfma_f32_16x16x32_bf16 v[110:113], v[196:199], v[150:153], v[110:113]
	ds_read_b128 v[224:227], v241 offset:20480
	v_mfma_f32_16x16x32_bf16 v[102:105], v[204:207], v[150:153], v[102:105]
	v_mfma_f32_16x16x32_bf16 v[94:97], v[196:199], v[158:161], v[94:97]
	ds_read_b128 v[228:231], v241 offset:21504
	v_mfma_f32_16x16x32_bf16 v[86:89], v[204:207], v[158:161], v[86:89]
	v_mfma_f32_16x16x32_bf16 v[78:81], v[196:199], v[180:183], v[78:81]
	ds_read_b128 v[232:235], v241 offset:22528
	v_mfma_f32_16x16x32_bf16 v[74:77], v[204:207], v[180:183], v[74:77]
	v_mfma_f32_16x16x32_bf16 v[70:73], v[196:199], v[188:191], v[70:73]
	ds_read_b128 v[246:249], v241 offset:23552
	v_mfma_f32_16x16x32_bf16 v[66:69], v[204:207], v[188:191], v[66:69]
	s_setprio 0
	s_barrier
	s_mov_b32 m0, s21
	s_add_u32 s94, s52, 0x80
	s_addc_u32 s95, s53, 0
	global_load_lds_dwordx4 v162, s[52:53]
	s_mov_b32 m0, s59
	s_nop 0
	global_load_lds_dwordx4 v164, s[52:53]
	s_waitcnt vmcnt(8)
	s_barrier
	s_waitcnt lgkmcnt(0)
	s_setprio 1
	v_mfma_f32_16x16x32_bf16 v[62:65], v[130:133], v[208:211], 0
	ds_read_b128 v[146:149], v241 offset:32768
	v_mfma_f32_16x16x32_bf16 v[58:61], v[138:141], v[208:211], 0
	v_mfma_f32_16x16x32_bf16 v[54:57], v[130:133], v[216:219], 0
	ds_read_b128 v[150:153], v241 offset:33792
	v_mfma_f32_16x16x32_bf16 v[50:53], v[138:141], v[216:219], 0
	v_mfma_f32_16x16x32_bf16 v[42:45], v[130:133], v[224:227], 0
	ds_read_b128 v[154:157], v241 offset:34816
	v_mfma_f32_16x16x32_bf16 v[34:37], v[138:141], v[224:227], 0
	v_mfma_f32_16x16x32_bf16 v[26:29], v[130:133], v[232:235], 0
	ds_read_b128 v[158:161], v241 offset:35840
	v_mfma_f32_16x16x32_bf16 v[18:21], v[138:141], v[232:235], 0
	v_mfma_f32_16x16x32_bf16 v[62:65], v[134:137], v[212:215], v[62:65]
	ds_read_b128 v[176:179], v241 offset:36864
	v_mfma_f32_16x16x32_bf16 v[58:61], v[142:145], v[212:215], v[58:61]
	v_mfma_f32_16x16x32_bf16 v[54:57], v[134:137], v[220:223], v[54:57]
	ds_read_b128 v[180:183], v241 offset:37888
	v_mfma_f32_16x16x32_bf16 v[50:53], v[142:145], v[220:223], v[50:53]
	v_mfma_f32_16x16x32_bf16 v[42:45], v[134:137], v[228:231], v[42:45]
	ds_read_b128 v[184:187], v241 offset:38912
	v_mfma_f32_16x16x32_bf16 v[34:37], v[142:145], v[228:231], v[34:37]
	v_mfma_f32_16x16x32_bf16 v[26:29], v[134:137], v[246:249], v[26:29]
	ds_read_b128 v[188:191], v241 offset:39936
	v_mfma_f32_16x16x32_bf16 v[18:21], v[142:145], v[246:249], v[18:21]
	s_setprio 0
	s_barrier
	s_add_u32 s82, s50, 0x80000
	s_addc_u32 s83, s51, 0
	s_add_i32 s81, s69, s56
	s_mov_b32 m0, s81
	s_nop 0
	global_load_lds_dwordx4 v162, s[82:83]
	s_add_i32 m0, s81, 0x2000
	s_nop 0
	global_load_lds_dwordx4 v164, s[82:83]
	s_waitcnt vmcnt(10)
	s_barrier
	s_waitcnt lgkmcnt(0)
	s_setprio 1
	v_mfma_f32_16x16x32_bf16 v[46:49], v[192:195], v[208:211], 0
	ds_read_b128 v[130:133], v168
	v_mfma_f32_16x16x32_bf16 v[38:41], v[200:203], v[208:211], 0
	v_mfma_f32_16x16x32_bf16 v[30:33], v[192:195], v[216:219], 0
	v_mfma_f32_16x16x32_bf16 v[22:25], v[200:203], v[216:219], 0
	v_mfma_f32_16x16x32_bf16 v[14:17], v[192:195], v[224:227], 0
	ds_read_b128 v[134:137], v168 offset:1024
	v_mfma_f32_16x16x32_bf16 v[10:13], v[200:203], v[224:227], 0
	v_mfma_f32_16x16x32_bf16 v[6:9], v[192:195], v[232:235], 0
	v_mfma_f32_16x16x32_bf16 v[2:5], v[200:203], v[232:235], 0
	v_mfma_f32_16x16x32_bf16 v[46:49], v[196:199], v[212:215], v[46:49]
	ds_read_b128 v[138:141], v168 offset:2048
	v_mfma_f32_16x16x32_bf16 v[38:41], v[204:207], v[212:215], v[38:41]
	v_mfma_f32_16x16x32_bf16 v[30:33], v[196:199], v[220:223], v[30:33]
	v_mfma_f32_16x16x32_bf16 v[22:25], v[204:207], v[220:223], v[22:25]
	v_mfma_f32_16x16x32_bf16 v[14:17], v[196:199], v[228:231], v[14:17]
	ds_read_b128 v[142:145], v168 offset:3072
	v_mfma_f32_16x16x32_bf16 v[10:13], v[204:207], v[228:231], v[10:13]
	v_mfma_f32_16x16x32_bf16 v[6:9], v[196:199], v[246:249], v[6:9]
	v_mfma_f32_16x16x32_bf16 v[2:5], v[204:207], v[246:249], v[2:5]
	s_setprio 0
	s_barrier
	s_add_i32 s81, 0, 0x18000
	s_add_u32 s52, s52, 0x80000
	s_addc_u32 s53, s53, 0
	s_mov_b32 m0, s60
	s_nop 0
	global_load_lds_dwordx4 v162, s[52:53]
	s_mov_b32 m0, s61
	s_nop 0
	global_load_lds_dwordx4 v164, s[52:53]
	s_waitcnt vmcnt(10)
	s_barrier
	s_waitcnt lgkmcnt(0)
	s_setprio 1
	v_mfma_f32_16x16x32_bf16 v[126:129], v[130:133], v[146:149], v[126:129]
	ds_read_b128 v[192:195], v169
	v_mfma_f32_16x16x32_bf16 v[122:125], v[138:141], v[146:149], v[122:125]
	v_mfma_f32_16x16x32_bf16 v[118:121], v[130:133], v[154:157], v[118:121]
	v_mfma_f32_16x16x32_bf16 v[114:117], v[138:141], v[154:157], v[114:117]
	v_mfma_f32_16x16x32_bf16 v[106:109], v[130:133], v[176:179], v[106:109]
	ds_read_b128 v[196:199], v169 offset:1024
	v_mfma_f32_16x16x32_bf16 v[98:101], v[138:141], v[176:179], v[98:101]
	v_mfma_f32_16x16x32_bf16 v[90:93], v[130:133], v[184:187], v[90:93]
	v_mfma_f32_16x16x32_bf16 v[82:85], v[138:141], v[184:187], v[82:85]
	v_mfma_f32_16x16x32_bf16 v[126:129], v[134:137], v[150:153], v[126:129]
	ds_read_b128 v[200:203], v169 offset:2048
	v_mfma_f32_16x16x32_bf16 v[122:125], v[142:145], v[150:153], v[122:125]
	v_mfma_f32_16x16x32_bf16 v[118:121], v[134:137], v[158:161], v[118:121]
	v_mfma_f32_16x16x32_bf16 v[114:117], v[142:145], v[158:161], v[114:117]
	v_mfma_f32_16x16x32_bf16 v[106:109], v[134:137], v[180:183], v[106:109]
	ds_read_b128 v[204:207], v169 offset:3072
	v_mfma_f32_16x16x32_bf16 v[98:101], v[142:145], v[180:183], v[98:101]
	v_mfma_f32_16x16x32_bf16 v[90:93], v[134:137], v[188:191], v[90:93]
	v_mfma_f32_16x16x32_bf16 v[82:85], v[142:145], v[188:191], v[82:85]
	s_setprio 0
	s_barrier
	s_add_i32 s52, 0, 0x1c000
	s_add_i32 s53, s81, s56
	s_mov_b32 m0, s53
	s_nop 0
	global_load_lds_dwordx4 v162, s[96:97]
	s_add_i32 m0, s53, 0x2000
	s_nop 0
	global_load_lds_dwordx4 v164, s[96:97]
	s_waitcnt vmcnt(10)
	s_barrier
	s_waitcnt lgkmcnt(0)
	s_setprio 1
	v_mfma_f32_16x16x32_bf16 v[110:113], v[192:195], v[146:149], v[110:113]
	ds_read_b128 v[208:211], v241 offset:49152
	v_mfma_f32_16x16x32_bf16 v[102:105], v[200:203], v[146:149], v[102:105]
	v_mfma_f32_16x16x32_bf16 v[94:97], v[192:195], v[154:157], v[94:97]
	ds_read_b128 v[212:215], v241 offset:50176
	v_mfma_f32_16x16x32_bf16 v[86:89], v[200:203], v[154:157], v[86:89]
	v_mfma_f32_16x16x32_bf16 v[78:81], v[192:195], v[176:179], v[78:81]
	ds_read_b128 v[216:219], v241 offset:51200
	v_mfma_f32_16x16x32_bf16 v[74:77], v[200:203], v[176:179], v[74:77]
	v_mfma_f32_16x16x32_bf16 v[70:73], v[192:195], v[184:187], v[70:73]
	ds_read_b128 v[220:223], v241 offset:52224
	v_mfma_f32_16x16x32_bf16 v[66:69], v[200:203], v[184:187], v[66:69]
	v_mfma_f32_16x16x32_bf16 v[110:113], v[196:199], v[150:153], v[110:113]
	ds_read_b128 v[224:227], v241 offset:53248
	v_mfma_f32_16x16x32_bf16 v[102:105], v[204:207], v[150:153], v[102:105]
	v_mfma_f32_16x16x32_bf16 v[94:97], v[196:199], v[158:161], v[94:97]
	ds_read_b128 v[228:231], v241 offset:54272
	v_mfma_f32_16x16x32_bf16 v[86:89], v[204:207], v[158:161], v[86:89]
	v_mfma_f32_16x16x32_bf16 v[78:81], v[196:199], v[180:183], v[78:81]
	ds_read_b128 v[232:235], v241 offset:55296
	v_mfma_f32_16x16x32_bf16 v[74:77], v[204:207], v[180:183], v[74:77]
	v_mfma_f32_16x16x32_bf16 v[70:73], v[196:199], v[188:191], v[70:73]
	ds_read_b128 v[246:249], v241 offset:56320
	v_mfma_f32_16x16x32_bf16 v[66:69], v[204:207], v[188:191], v[66:69]
	s_setprio 0
	s_barrier
	s_mov_b32 m0, s64
	s_nop 0
	global_load_lds_dwordx4 v162, s[94:95]
	s_mov_b32 m0, s65
	s_nop 0
	global_load_lds_dwordx4 v164, s[94:95]
	s_waitcnt vmcnt(8)
	s_barrier
	s_waitcnt lgkmcnt(0)
	s_setprio 1
	v_mfma_f32_16x16x32_bf16 v[62:65], v[130:133], v[208:211], v[62:65]
	ds_read_b128 v[146:149], v241
	v_mfma_f32_16x16x32_bf16 v[58:61], v[138:141], v[208:211], v[58:61]
	v_mfma_f32_16x16x32_bf16 v[54:57], v[130:133], v[216:219], v[54:57]
	ds_read_b128 v[150:153], v241 offset:1024
	v_mfma_f32_16x16x32_bf16 v[50:53], v[138:141], v[216:219], v[50:53]
	v_mfma_f32_16x16x32_bf16 v[42:45], v[130:133], v[224:227], v[42:45]
	ds_read_b128 v[154:157], v241 offset:2048
	v_mfma_f32_16x16x32_bf16 v[34:37], v[138:141], v[224:227], v[34:37]
	v_mfma_f32_16x16x32_bf16 v[26:29], v[130:133], v[232:235], v[26:29]
	ds_read_b128 v[158:161], v241 offset:3072
	v_mfma_f32_16x16x32_bf16 v[18:21], v[138:141], v[232:235], v[18:21]
	v_mfma_f32_16x16x32_bf16 v[62:65], v[134:137], v[212:215], v[62:65]
	ds_read_b128 v[176:179], v241 offset:4096
	v_mfma_f32_16x16x32_bf16 v[58:61], v[142:145], v[212:215], v[58:61]
	v_mfma_f32_16x16x32_bf16 v[54:57], v[134:137], v[220:223], v[54:57]
	ds_read_b128 v[180:183], v241 offset:5120
	v_mfma_f32_16x16x32_bf16 v[50:53], v[142:145], v[220:223], v[50:53]
	v_mfma_f32_16x16x32_bf16 v[42:45], v[134:137], v[228:231], v[42:45]
	ds_read_b128 v[184:187], v241 offset:6144
	v_mfma_f32_16x16x32_bf16 v[34:37], v[142:145], v[228:231], v[34:37]
	v_mfma_f32_16x16x32_bf16 v[26:29], v[134:137], v[246:249], v[26:29]
	ds_read_b128 v[188:191], v241 offset:7168
	v_mfma_f32_16x16x32_bf16 v[18:21], v[142:145], v[246:249], v[18:21]
	s_setprio 0
	s_barrier
	s_add_u32 s50, s50, 0x80080
	s_addc_u32 s51, s51, 0
	s_add_i32 s52, s52, s56
	s_mov_b32 m0, s52
	s_nop 0
	global_load_lds_dwordx4 v162, s[50:51]
	s_add_i32 m0, s52, 0x2000
	s_nop 0
	global_load_lds_dwordx4 v164, s[50:51]
	s_waitcnt vmcnt(10)
	s_barrier
	s_waitcnt lgkmcnt(0)
	s_setprio 1
	v_mfma_f32_16x16x32_bf16 v[46:49], v[192:195], v[208:211], v[46:49]
	ds_read_b128 v[130:133], v240
	v_mfma_f32_16x16x32_bf16 v[38:41], v[200:203], v[208:211], v[38:41]
	v_mfma_f32_16x16x32_bf16 v[30:33], v[192:195], v[216:219], v[30:33]
	v_mfma_f32_16x16x32_bf16 v[22:25], v[200:203], v[216:219], v[22:25]
	v_mfma_f32_16x16x32_bf16 v[14:17], v[192:195], v[224:227], v[14:17]
	ds_read_b128 v[134:137], v240 offset:1024
	v_mfma_f32_16x16x32_bf16 v[10:13], v[200:203], v[224:227], v[10:13]
	v_mfma_f32_16x16x32_bf16 v[6:9], v[192:195], v[232:235], v[6:9]
	v_mfma_f32_16x16x32_bf16 v[2:5], v[200:203], v[232:235], v[2:5]
	v_mfma_f32_16x16x32_bf16 v[46:49], v[196:199], v[212:215], v[46:49]
	ds_read_b128 v[138:141], v240 offset:2048
	v_mfma_f32_16x16x32_bf16 v[38:41], v[204:207], v[212:215], v[38:41]
	v_mfma_f32_16x16x32_bf16 v[30:33], v[196:199], v[220:223], v[30:33]
	v_mfma_f32_16x16x32_bf16 v[22:25], v[204:207], v[220:223], v[22:25]
	v_mfma_f32_16x16x32_bf16 v[14:17], v[196:199], v[228:231], v[14:17]
	ds_read_b128 v[142:145], v240 offset:3072
	v_mfma_f32_16x16x32_bf16 v[10:13], v[204:207], v[228:231], v[10:13]
	v_mfma_f32_16x16x32_bf16 v[6:9], v[196:199], v[246:249], v[6:9]
	v_mfma_f32_16x16x32_bf16 v[2:5], v[204:207], v[246:249], v[2:5]
	s_setprio 0
	s_add_i32 s80, s80, 2
	s_add_u32 s48, s48, 0x100
	s_addc_u32 s49, s49, 0
	s_add_u32 s74, s74, 0x100
	s_addc_u32 s75, s75, 0
	s_cmp_gt_u32 s80, s87
	s_barrier
	s_cbranch_scc0 .LBB0_1098
	s_branch .Lp8_loop_exit

.Lp8_loop_exit:
	v_lshl_or_b32 v176, s46, 7, v239
	s_cmp_gt_i32 s20, 63
	v_ashrrev_i32_e32 v177, 31, v176
	s_mov_b64 s[46:47], -1
	s_cbranch_scc1 .LBB0_1141
	v_add_u32_e32 v251, s86, v250
	ds_read_b128 v[130:133], v251
	ds_read_b128 v[146:149], v251 offset:512
	ds_read_b128 v[134:137], v251 offset:1024
	ds_read_b128 v[150:153], v251 offset:1536
	ds_read_b128 v[138:141], v251 offset:2048
	ds_read_b128 v[154:157], v251 offset:2560
	ds_read_b128 v[142:145], v251 offset:3072
	ds_read_b128 v[158:161], v251 offset:3584
	ds_read_b128 v[178:181], v251 offset:64
	ds_read_b128 v[194:197], v251 offset:576
	ds_read_b128 v[182:185], v251 offset:1088
	ds_read_b128 v[198:201], v251 offset:1600
	ds_read_b128 v[186:189], v251 offset:2112
	ds_read_b128 v[202:205], v251 offset:2624
	ds_read_b128 v[190:193], v251 offset:3136
	ds_read_b128 v[206:209], v251 offset:3648
	s_lshl_b32 s39, s20, 2
	s_add_i32 s39, s39, s55
	s_mov_b32 s96, 0x2c000
	s_mov_b32 s97, 0
	s_mov_b32 s48, 0xbfb8aa3b
	v_mov_b32_e32 v211, 0
	v_mov_b32_e32 v213, 0
	v_mov_b32_e32 v215, 0
	v_mov_b32_e32 v217, 0
	v_mov_b32_e32 v219, 0
	v_lshlrev_b32_e32 v243, 2, v176
	v_lshlrev_b32_e32 v244, 1, v176
	v_mul_u32_u24_e32 v210, 0x2c00, v1
	v_add_u32_e32 v210, v210, v244
	v_mul_u32_u24_e32 v212, 0xb000, v1
	v_add_u32_e32 v212, v212, v243
	v_add_u32_e32 v214, 0x5800, v212
	v_mul_i32_i24_e32 v216, 0xb000, v237
	v_add_u32_e32 v216, v216, v243
	v_add_u32_e32 v218, 0x5800, v216
	s_waitcnt lgkmcnt(8)
	s_add_i32 s84, s39, 0
	s_mul_i32 s85, s84, 0xb0000
	s_add_u32 s94, s22, s85
	s_addc_u32 s95, s23, 0
	v_lshl_add_u64 v[220:221], s[94:95], 0, v[210:211]
	s_mul_i32 s85, s84, 0x16000
	s_add_u32 s94, s24, s85
	s_addc_u32 s95, s25, 0
	v_lshl_add_u64 v[222:223], s[94:95], 0, v[212:213]
	v_lshl_add_u64 v[246:247], s[94:95], 0, v[214:215]
	s_and_saveexec_b64 s[46:47], s[4:5]
	global_store_dwordx4 v[222:223], v[126:129], off
	global_store_dwordx4 v[246:247], v[110:113], off
	s_or_b64 exec, exec, s[46:47]
	v_pk_fma_f32 v[224:225], v[126:127], v[138:139], v[142:143]
	v_pk_fma_f32 v[226:227], v[128:129], v[140:141], v[144:145]
	v_pk_fma_f32 v[228:229], v[110:111], v[154:155], v[158:159]
	v_pk_fma_f32 v[230:231], v[112:113], v[156:157], v[160:161]
	v_fmac_f32_dpp v224, v126, v134 row_shr:1 row_mask:0xf bank_mask:0xf bound_ctrl:1
	v_fmac_f32_dpp v225, v127, v135 row_shr:1 row_mask:0xf bank_mask:0xf bound_ctrl:1
	v_fmac_f32_dpp v226, v128, v136 row_shr:1 row_mask:0xf bank_mask:0xf bound_ctrl:1
	v_fmac_f32_dpp v227, v129, v137 row_shr:1 row_mask:0xf bank_mask:0xf bound_ctrl:1
	v_fmac_f32_dpp v228, v110, v150 row_shr:1 row_mask:0xf bank_mask:0xf bound_ctrl:1
	v_fmac_f32_dpp v229, v111, v151 row_shr:1 row_mask:0xf bank_mask:0xf bound_ctrl:1
	v_fmac_f32_dpp v230, v112, v152 row_shr:1 row_mask:0xf bank_mask:0xf bound_ctrl:1
	v_fmac_f32_dpp v231, v113, v153 row_shr:1 row_mask:0xf bank_mask:0xf bound_ctrl:1
	v_fmac_f32_dpp v224, v126, v130 row_shr:2 row_mask:0xf bank_mask:0xf bound_ctrl:1
	v_fmac_f32_dpp v225, v127, v131 row_shr:2 row_mask:0xf bank_mask:0xf bound_ctrl:1
	v_fmac_f32_dpp v226, v128, v132 row_shr:2 row_mask:0xf bank_mask:0xf bound_ctrl:1
	v_fmac_f32_dpp v227, v129, v133 row_shr:2 row_mask:0xf bank_mask:0xf bound_ctrl:1
	v_fmac_f32_dpp v228, v110, v146 row_shr:2 row_mask:0xf bank_mask:0xf bound_ctrl:1
	v_fmac_f32_dpp v229, v111, v147 row_shr:2 row_mask:0xf bank_mask:0xf bound_ctrl:1
	v_fmac_f32_dpp v230, v112, v148 row_shr:2 row_mask:0xf bank_mask:0xf bound_ctrl:1
	v_fmac_f32_dpp v231, v113, v149 row_shr:2 row_mask:0xf bank_mask:0xf bound_ctrl:1
	v_pk_mul_f32 v[232:233], v[224:225], s[48:49] op_sel_hi:[1,0]
	v_pk_mul_f32 v[234:235], v[226:227], s[48:49] op_sel_hi:[1,0]
	v_exp_f32_e32 v232, v232
	v_exp_f32_e32 v233, v233
	v_exp_f32_e32 v234, v234
	v_exp_f32_e32 v235, v235
	v_pk_add_f32 v[232:233], v[232:233], 1.0 op_sel_hi:[1,0]
	v_pk_add_f32 v[234:235], v[234:235], 1.0 op_sel_hi:[1,0]
	v_rcp_f32_e32 v232, v232
	v_rcp_f32_e32 v233, v233
	v_rcp_f32_e32 v234, v234
	v_rcp_f32_e32 v235, v235
	v_pk_mul_f32 v[224:225], v[224:225], v[232:233]
	v_pk_mul_f32 v[226:227], v[226:227], v[234:235]
	v_pk_mul_f32 v[224:225], v[224:225], v[228:229]
	v_pk_mul_f32 v[226:227], v[226:227], v[230:231]
	v_cvt_pk_bf16_f32 v168, v224, v225
	v_cvt_pk_bf16_f32 v169, v226, v227
	s_and_saveexec_b64 s[46:47], s[8:9]
	global_store_dwordx2 v[220:221], v[168:169], off
	s_or_b64 exec, exec, s[46:47]
	v_pk_fma_f32 v[224:225], v[118:119], v[138:139], v[142:143]
	v_pk_fma_f32 v[226:227], v[120:121], v[140:141], v[144:145]
	v_pk_fma_f32 v[228:229], v[94:95], v[154:155], v[158:159]
	v_pk_fma_f32 v[230:231], v[96:97], v[156:157], v[160:161]
	v_fmac_f32_dpp v224, v118, v134 row_shr:1 row_mask:0xf bank_mask:0xf bound_ctrl:1
	v_fmac_f32_dpp v225, v119, v135 row_shr:1 row_mask:0xf bank_mask:0xf bound_ctrl:1
	v_fmac_f32_dpp v226, v120, v136 row_shr:1 row_mask:0xf bank_mask:0xf bound_ctrl:1
	v_fmac_f32_dpp v227, v121, v137 row_shr:1 row_mask:0xf bank_mask:0xf bound_ctrl:1
	v_fmac_f32_dpp v228, v94, v150 row_shr:1 row_mask:0xf bank_mask:0xf bound_ctrl:1
	v_fmac_f32_dpp v229, v95, v151 row_shr:1 row_mask:0xf bank_mask:0xf bound_ctrl:1
	v_fmac_f32_dpp v230, v96, v152 row_shr:1 row_mask:0xf bank_mask:0xf bound_ctrl:1
	v_fmac_f32_dpp v231, v97, v153 row_shr:1 row_mask:0xf bank_mask:0xf bound_ctrl:1
	v_fmac_f32_dpp v224, v118, v130 row_shr:2 row_mask:0xf bank_mask:0xf bound_ctrl:1
	v_fmac_f32_dpp v225, v119, v131 row_shr:2 row_mask:0xf bank_mask:0xf bound_ctrl:1
	v_fmac_f32_dpp v226, v120, v132 row_shr:2 row_mask:0xf bank_mask:0xf bound_ctrl:1
	v_fmac_f32_dpp v227, v121, v133 row_shr:2 row_mask:0xf bank_mask:0xf bound_ctrl:1
	v_fmac_f32_dpp v228, v94, v146 row_shr:2 row_mask:0xf bank_mask:0xf bound_ctrl:1
	v_fmac_f32_dpp v229, v95, v147 row_shr:2 row_mask:0xf bank_mask:0xf bound_ctrl:1
	v_fmac_f32_dpp v230, v96, v148 row_shr:2 row_mask:0xf bank_mask:0xf bound_ctrl:1
	v_fmac_f32_dpp v231, v97, v149 row_shr:2 row_mask:0xf bank_mask:0xf bound_ctrl:1
	v_fmac_f32_dpp v224, v126, v134 row_shl:15 row_mask:0xf bank_mask:0xf bound_ctrl:1
	v_fmac_f32_dpp v225, v127, v135 row_shl:15 row_mask:0xf bank_mask:0xf bound_ctrl:1
	v_fmac_f32_dpp v226, v128, v136 row_shl:15 row_mask:0xf bank_mask:0xf bound_ctrl:1
	v_fmac_f32_dpp v227, v129, v137 row_shl:15 row_mask:0xf bank_mask:0xf bound_ctrl:1
	v_fmac_f32_dpp v228, v110, v150 row_shl:15 row_mask:0xf bank_mask:0xf bound_ctrl:1
	v_fmac_f32_dpp v229, v111, v151 row_shl:15 row_mask:0xf bank_mask:0xf bound_ctrl:1
	v_fmac_f32_dpp v230, v112, v152 row_shl:15 row_mask:0xf bank_mask:0xf bound_ctrl:1
	v_fmac_f32_dpp v231, v113, v153 row_shl:15 row_mask:0xf bank_mask:0xf bound_ctrl:1
	v_fmac_f32_dpp v224, v126, v130 row_shl:14 row_mask:0xf bank_mask:0xf bound_ctrl:1
	v_fmac_f32_dpp v225, v127, v131 row_shl:14 row_mask:0xf bank_mask:0xf bound_ctrl:1
	v_fmac_f32_dpp v226, v128, v132 row_shl:14 row_mask:0xf bank_mask:0xf bound_ctrl:1
	v_fmac_f32_dpp v227, v129, v133 row_shl:14 row_mask:0xf bank_mask:0xf bound_ctrl:1
	v_fmac_f32_dpp v228, v110, v146 row_shl:14 row_mask:0xf bank_mask:0xf bound_ctrl:1
	v_fmac_f32_dpp v229, v111, v147 row_shl:14 row_mask:0xf bank_mask:0xf bound_ctrl:1
	v_fmac_f32_dpp v230, v112, v148 row_shl:14 row_mask:0xf bank_mask:0xf bound_ctrl:1
	v_fmac_f32_dpp v231, v113, v149 row_shl:14 row_mask:0xf bank_mask:0xf bound_ctrl:1
	v_pk_mul_f32 v[232:233], v[224:225], s[48:49] op_sel_hi:[1,0]
	v_pk_mul_f32 v[234:235], v[226:227], s[48:49] op_sel_hi:[1,0]
	v_exp_f32_e32 v232, v232
	v_exp_f32_e32 v233, v233
	v_exp_f32_e32 v234, v234
	v_exp_f32_e32 v235, v235
	v_pk_add_f32 v[232:233], v[232:233], 1.0 op_sel_hi:[1,0]
	v_pk_add_f32 v[234:235], v[234:235], 1.0 op_sel_hi:[1,0]
	v_rcp_f32_e32 v232, v232
	v_rcp_f32_e32 v233, v233
	v_rcp_f32_e32 v234, v234
	v_rcp_f32_e32 v235, v235
	v_lshl_add_u64 v[220:221], v[220:221], 0, s[96:97]
	v_pk_mul_f32 v[224:225], v[224:225], v[232:233]
	v_pk_mul_f32 v[226:227], v[226:227], v[234:235]
	v_pk_mul_f32 v[224:225], v[224:225], v[228:229]
	v_pk_mul_f32 v[226:227], v[226:227], v[230:231]
	v_cvt_pk_bf16_f32 v168, v224, v225
	v_cvt_pk_bf16_f32 v169, v226, v227
	global_store_dwordx2 v[220:221], v[168:169], off
	v_pk_fma_f32 v[224:225], v[106:107], v[138:139], v[142:143]
	v_pk_fma_f32 v[226:227], v[108:109], v[140:141], v[144:145]
	v_pk_fma_f32 v[228:229], v[78:79], v[154:155], v[158:159]
	v_pk_fma_f32 v[230:231], v[80:81], v[156:157], v[160:161]
	v_fmac_f32_dpp v224, v106, v134 row_shr:1 row_mask:0xf bank_mask:0xf bound_ctrl:1
	v_fmac_f32_dpp v225, v107, v135 row_shr:1 row_mask:0xf bank_mask:0xf bound_ctrl:1
	v_fmac_f32_dpp v226, v108, v136 row_shr:1 row_mask:0xf bank_mask:0xf bound_ctrl:1
	v_fmac_f32_dpp v227, v109, v137 row_shr:1 row_mask:0xf bank_mask:0xf bound_ctrl:1
	v_fmac_f32_dpp v228, v78, v150 row_shr:1 row_mask:0xf bank_mask:0xf bound_ctrl:1
	v_fmac_f32_dpp v229, v79, v151 row_shr:1 row_mask:0xf bank_mask:0xf bound_ctrl:1
	v_fmac_f32_dpp v230, v80, v152 row_shr:1 row_mask:0xf bank_mask:0xf bound_ctrl:1
	v_fmac_f32_dpp v231, v81, v153 row_shr:1 row_mask:0xf bank_mask:0xf bound_ctrl:1
	v_fmac_f32_dpp v224, v106, v130 row_shr:2 row_mask:0xf bank_mask:0xf bound_ctrl:1
	v_fmac_f32_dpp v225, v107, v131 row_shr:2 row_mask:0xf bank_mask:0xf bound_ctrl:1
	v_fmac_f32_dpp v226, v108, v132 row_shr:2 row_mask:0xf bank_mask:0xf bound_ctrl:1
	v_fmac_f32_dpp v227, v109, v133 row_shr:2 row_mask:0xf bank_mask:0xf bound_ctrl:1
	v_fmac_f32_dpp v228, v78, v146 row_shr:2 row_mask:0xf bank_mask:0xf bound_ctrl:1
	v_fmac_f32_dpp v229, v79, v147 row_shr:2 row_mask:0xf bank_mask:0xf bound_ctrl:1
	v_fmac_f32_dpp v230, v80, v148 row_shr:2 row_mask:0xf bank_mask:0xf bound_ctrl:1
	v_fmac_f32_dpp v231, v81, v149 row_shr:2 row_mask:0xf bank_mask:0xf bound_ctrl:1
	v_fmac_f32_dpp v224, v118, v134 row_shl:15 row_mask:0xf bank_mask:0xf bound_ctrl:1
	v_fmac_f32_dpp v225, v119, v135 row_shl:15 row_mask:0xf bank_mask:0xf bound_ctrl:1
	v_fmac_f32_dpp v226, v120, v136 row_shl:15 row_mask:0xf bank_mask:0xf bound_ctrl:1
	v_fmac_f32_dpp v227, v121, v137 row_shl:15 row_mask:0xf bank_mask:0xf bound_ctrl:1
	v_fmac_f32_dpp v228, v94, v150 row_shl:15 row_mask:0xf bank_mask:0xf bound_ctrl:1
	v_fmac_f32_dpp v229, v95, v151 row_shl:15 row_mask:0xf bank_mask:0xf bound_ctrl:1
	v_fmac_f32_dpp v230, v96, v152 row_shl:15 row_mask:0xf bank_mask:0xf bound_ctrl:1
	v_fmac_f32_dpp v231, v97, v153 row_shl:15 row_mask:0xf bank_mask:0xf bound_ctrl:1
	v_fmac_f32_dpp v224, v118, v130 row_shl:14 row_mask:0xf bank_mask:0xf bound_ctrl:1
	v_fmac_f32_dpp v225, v119, v131 row_shl:14 row_mask:0xf bank_mask:0xf bound_ctrl:1
	v_fmac_f32_dpp v226, v120, v132 row_shl:14 row_mask:0xf bank_mask:0xf bound_ctrl:1
	v_fmac_f32_dpp v227, v121, v133 row_shl:14 row_mask:0xf bank_mask:0xf bound_ctrl:1
	v_fmac_f32_dpp v228, v94, v146 row_shl:14 row_mask:0xf bank_mask:0xf bound_ctrl:1
	v_fmac_f32_dpp v229, v95, v147 row_shl:14 row_mask:0xf bank_mask:0xf bound_ctrl:1
	v_fmac_f32_dpp v230, v96, v148 row_shl:14 row_mask:0xf bank_mask:0xf bound_ctrl:1
	v_fmac_f32_dpp v231, v97, v149 row_shl:14 row_mask:0xf bank_mask:0xf bound_ctrl:1
	v_pk_mul_f32 v[232:233], v[224:225], s[48:49] op_sel_hi:[1,0]
	v_pk_mul_f32 v[234:235], v[226:227], s[48:49] op_sel_hi:[1,0]
	v_exp_f32_e32 v232, v232
	v_exp_f32_e32 v233, v233
	v_exp_f32_e32 v234, v234
	v_exp_f32_e32 v235, v235
	v_pk_add_f32 v[232:233], v[232:233], 1.0 op_sel_hi:[1,0]
	v_pk_add_f32 v[234:235], v[234:235], 1.0 op_sel_hi:[1,0]
	v_rcp_f32_e32 v232, v232
	v_rcp_f32_e32 v233, v233
	v_rcp_f32_e32 v234, v234
	v_rcp_f32_e32 v235, v235
	v_lshl_add_u64 v[220:221], v[220:221], 0, s[96:97]
	v_pk_mul_f32 v[224:225], v[224:225], v[232:233]
	v_pk_mul_f32 v[226:227], v[226:227], v[234:235]
	v_pk_mul_f32 v[224:225], v[224:225], v[228:229]
	v_pk_mul_f32 v[226:227], v[226:227], v[230:231]
	v_cvt_pk_bf16_f32 v168, v224, v225
	v_cvt_pk_bf16_f32 v169, v226, v227
	global_store_dwordx2 v[220:221], v[168:169], off
	s_add_u32 s94, s26, s85
	s_addc_u32 s95, s27, 0
	v_lshl_add_u64 v[222:223], s[94:95], 0, v[216:217]
	v_lshl_add_u64 v[246:247], s[94:95], 0, v[218:219]
	s_and_saveexec_b64 s[46:47], s[6:7]
	global_store_dwordx4 v[222:223], v[90:93], off
	global_store_dwordx4 v[246:247], v[70:73], off
	s_or_b64 exec, exec, s[46:47]
	v_pk_fma_f32 v[224:225], v[90:91], v[138:139], v[142:143]
	v_pk_fma_f32 v[226:227], v[92:93], v[140:141], v[144:145]
	v_pk_fma_f32 v[228:229], v[70:71], v[154:155], v[158:159]
	v_pk_fma_f32 v[230:231], v[72:73], v[156:157], v[160:161]
	v_fmac_f32_dpp v224, v90, v134 row_shr:1 row_mask:0xf bank_mask:0xf bound_ctrl:1
	v_fmac_f32_dpp v225, v91, v135 row_shr:1 row_mask:0xf bank_mask:0xf bound_ctrl:1
	v_fmac_f32_dpp v226, v92, v136 row_shr:1 row_mask:0xf bank_mask:0xf bound_ctrl:1
	v_fmac_f32_dpp v227, v93, v137 row_shr:1 row_mask:0xf bank_mask:0xf bound_ctrl:1
	v_fmac_f32_dpp v228, v70, v150 row_shr:1 row_mask:0xf bank_mask:0xf bound_ctrl:1
	v_fmac_f32_dpp v229, v71, v151 row_shr:1 row_mask:0xf bank_mask:0xf bound_ctrl:1
	v_fmac_f32_dpp v230, v72, v152 row_shr:1 row_mask:0xf bank_mask:0xf bound_ctrl:1
	v_fmac_f32_dpp v231, v73, v153 row_shr:1 row_mask:0xf bank_mask:0xf bound_ctrl:1
	v_fmac_f32_dpp v224, v90, v130 row_shr:2 row_mask:0xf bank_mask:0xf bound_ctrl:1
	v_fmac_f32_dpp v225, v91, v131 row_shr:2 row_mask:0xf bank_mask:0xf bound_ctrl:1
	v_fmac_f32_dpp v226, v92, v132 row_shr:2 row_mask:0xf bank_mask:0xf bound_ctrl:1
	v_fmac_f32_dpp v227, v93, v133 row_shr:2 row_mask:0xf bank_mask:0xf bound_ctrl:1
	v_fmac_f32_dpp v228, v70, v146 row_shr:2 row_mask:0xf bank_mask:0xf bound_ctrl:1
	v_fmac_f32_dpp v229, v71, v147 row_shr:2 row_mask:0xf bank_mask:0xf bound_ctrl:1
	v_fmac_f32_dpp v230, v72, v148 row_shr:2 row_mask:0xf bank_mask:0xf bound_ctrl:1
	v_fmac_f32_dpp v231, v73, v149 row_shr:2 row_mask:0xf bank_mask:0xf bound_ctrl:1
	v_fmac_f32_dpp v224, v106, v134 row_shl:15 row_mask:0xf bank_mask:0xf bound_ctrl:1
	v_fmac_f32_dpp v225, v107, v135 row_shl:15 row_mask:0xf bank_mask:0xf bound_ctrl:1
	v_fmac_f32_dpp v226, v108, v136 row_shl:15 row_mask:0xf bank_mask:0xf bound_ctrl:1
	v_fmac_f32_dpp v227, v109, v137 row_shl:15 row_mask:0xf bank_mask:0xf bound_ctrl:1
	v_fmac_f32_dpp v228, v78, v150 row_shl:15 row_mask:0xf bank_mask:0xf bound_ctrl:1
	v_fmac_f32_dpp v229, v79, v151 row_shl:15 row_mask:0xf bank_mask:0xf bound_ctrl:1
	v_fmac_f32_dpp v230, v80, v152 row_shl:15 row_mask:0xf bank_mask:0xf bound_ctrl:1
	v_fmac_f32_dpp v231, v81, v153 row_shl:15 row_mask:0xf bank_mask:0xf bound_ctrl:1
	v_fmac_f32_dpp v224, v106, v130 row_shl:14 row_mask:0xf bank_mask:0xf bound_ctrl:1
	v_fmac_f32_dpp v225, v107, v131 row_shl:14 row_mask:0xf bank_mask:0xf bound_ctrl:1
	v_fmac_f32_dpp v226, v108, v132 row_shl:14 row_mask:0xf bank_mask:0xf bound_ctrl:1
	v_fmac_f32_dpp v227, v109, v133 row_shl:14 row_mask:0xf bank_mask:0xf bound_ctrl:1
	v_fmac_f32_dpp v228, v78, v146 row_shl:14 row_mask:0xf bank_mask:0xf bound_ctrl:1
	v_fmac_f32_dpp v229, v79, v147 row_shl:14 row_mask:0xf bank_mask:0xf bound_ctrl:1
	v_fmac_f32_dpp v230, v80, v148 row_shl:14 row_mask:0xf bank_mask:0xf bound_ctrl:1
	v_fmac_f32_dpp v231, v81, v149 row_shl:14 row_mask:0xf bank_mask:0xf bound_ctrl:1
	v_pk_mul_f32 v[232:233], v[224:225], s[48:49] op_sel_hi:[1,0]
	v_pk_mul_f32 v[234:235], v[226:227], s[48:49] op_sel_hi:[1,0]
	v_exp_f32_e32 v232, v232
	v_exp_f32_e32 v233, v233
	v_exp_f32_e32 v234, v234
	v_exp_f32_e32 v235, v235
	v_pk_add_f32 v[232:233], v[232:233], 1.0 op_sel_hi:[1,0]
	v_pk_add_f32 v[234:235], v[234:235], 1.0 op_sel_hi:[1,0]
	v_rcp_f32_e32 v232, v232
	v_rcp_f32_e32 v233, v233
	v_rcp_f32_e32 v234, v234
	v_rcp_f32_e32 v235, v235
	v_lshl_add_u64 v[220:221], v[220:221], 0, s[96:97]
	v_pk_mul_f32 v[224:225], v[224:225], v[232:233]
	v_pk_mul_f32 v[226:227], v[226:227], v[234:235]
	v_pk_mul_f32 v[224:225], v[224:225], v[228:229]
	v_pk_mul_f32 v[226:227], v[226:227], v[230:231]
	v_cvt_pk_bf16_f32 v168, v224, v225
	v_cvt_pk_bf16_f32 v169, v226, v227
	global_store_dwordx2 v[220:221], v[168:169], off
	s_add_i32 s84, s39, 2
	s_mul_i32 s85, s84, 0xb0000
	s_add_u32 s94, s22, s85
	s_addc_u32 s95, s23, 0
	v_lshl_add_u64 v[220:221], s[94:95], 0, v[210:211]
	s_mul_i32 s85, s84, 0x16000
	s_add_u32 s94, s24, s85
	s_addc_u32 s95, s25, 0
	v_lshl_add_u64 v[222:223], s[94:95], 0, v[212:213]
	v_lshl_add_u64 v[246:247], s[94:95], 0, v[214:215]
	s_and_saveexec_b64 s[46:47], s[4:5]
	global_store_dwordx4 v[222:223], v[62:65], off
	global_store_dwordx4 v[246:247], v[46:49], off
	s_or_b64 exec, exec, s[46:47]
	v_pk_fma_f32 v[224:225], v[62:63], v[138:139], v[142:143]
	v_pk_fma_f32 v[226:227], v[64:65], v[140:141], v[144:145]
	v_pk_fma_f32 v[228:229], v[46:47], v[154:155], v[158:159]
	v_pk_fma_f32 v[230:231], v[48:49], v[156:157], v[160:161]
	v_fmac_f32_dpp v224, v62, v134 row_shr:1 row_mask:0xf bank_mask:0xf bound_ctrl:1
	v_fmac_f32_dpp v225, v63, v135 row_shr:1 row_mask:0xf bank_mask:0xf bound_ctrl:1
	v_fmac_f32_dpp v226, v64, v136 row_shr:1 row_mask:0xf bank_mask:0xf bound_ctrl:1
	v_fmac_f32_dpp v227, v65, v137 row_shr:1 row_mask:0xf bank_mask:0xf bound_ctrl:1
	v_fmac_f32_dpp v228, v46, v150 row_shr:1 row_mask:0xf bank_mask:0xf bound_ctrl:1
	v_fmac_f32_dpp v229, v47, v151 row_shr:1 row_mask:0xf bank_mask:0xf bound_ctrl:1
	v_fmac_f32_dpp v230, v48, v152 row_shr:1 row_mask:0xf bank_mask:0xf bound_ctrl:1
	v_fmac_f32_dpp v231, v49, v153 row_shr:1 row_mask:0xf bank_mask:0xf bound_ctrl:1
	v_fmac_f32_dpp v224, v62, v130 row_shr:2 row_mask:0xf bank_mask:0xf bound_ctrl:1
	v_fmac_f32_dpp v225, v63, v131 row_shr:2 row_mask:0xf bank_mask:0xf bound_ctrl:1
	v_fmac_f32_dpp v226, v64, v132 row_shr:2 row_mask:0xf bank_mask:0xf bound_ctrl:1
	v_fmac_f32_dpp v227, v65, v133 row_shr:2 row_mask:0xf bank_mask:0xf bound_ctrl:1
	v_fmac_f32_dpp v228, v46, v146 row_shr:2 row_mask:0xf bank_mask:0xf bound_ctrl:1
	v_fmac_f32_dpp v229, v47, v147 row_shr:2 row_mask:0xf bank_mask:0xf bound_ctrl:1
	v_fmac_f32_dpp v230, v48, v148 row_shr:2 row_mask:0xf bank_mask:0xf bound_ctrl:1
	v_fmac_f32_dpp v231, v49, v149 row_shr:2 row_mask:0xf bank_mask:0xf bound_ctrl:1
	v_pk_mul_f32 v[232:233], v[224:225], s[48:49] op_sel_hi:[1,0]
	v_pk_mul_f32 v[234:235], v[226:227], s[48:49] op_sel_hi:[1,0]
	v_exp_f32_e32 v232, v232
	v_exp_f32_e32 v233, v233
	v_exp_f32_e32 v234, v234
	v_exp_f32_e32 v235, v235
	v_pk_add_f32 v[232:233], v[232:233], 1.0 op_sel_hi:[1,0]
	v_pk_add_f32 v[234:235], v[234:235], 1.0 op_sel_hi:[1,0]
	v_rcp_f32_e32 v232, v232
	v_rcp_f32_e32 v233, v233
	v_rcp_f32_e32 v234, v234
	v_rcp_f32_e32 v235, v235
	v_pk_mul_f32 v[224:225], v[224:225], v[232:233]
	v_pk_mul_f32 v[226:227], v[226:227], v[234:235]
	v_pk_mul_f32 v[224:225], v[224:225], v[228:229]
	v_pk_mul_f32 v[226:227], v[226:227], v[230:231]
	v_cvt_pk_bf16_f32 v168, v224, v225
	v_cvt_pk_bf16_f32 v169, v226, v227
	s_and_saveexec_b64 s[46:47], s[8:9]
	global_store_dwordx2 v[220:221], v[168:169], off
	s_or_b64 exec, exec, s[46:47]
	v_pk_fma_f32 v[224:225], v[54:55], v[138:139], v[142:143]
	v_pk_fma_f32 v[226:227], v[56:57], v[140:141], v[144:145]
	v_pk_fma_f32 v[228:229], v[30:31], v[154:155], v[158:159]
	v_pk_fma_f32 v[230:231], v[32:33], v[156:157], v[160:161]
	v_fmac_f32_dpp v224, v54, v134 row_shr:1 row_mask:0xf bank_mask:0xf bound_ctrl:1
	v_fmac_f32_dpp v225, v55, v135 row_shr:1 row_mask:0xf bank_mask:0xf bound_ctrl:1
	v_fmac_f32_dpp v226, v56, v136 row_shr:1 row_mask:0xf bank_mask:0xf bound_ctrl:1
	v_fmac_f32_dpp v227, v57, v137 row_shr:1 row_mask:0xf bank_mask:0xf bound_ctrl:1
	v_fmac_f32_dpp v228, v30, v150 row_shr:1 row_mask:0xf bank_mask:0xf bound_ctrl:1
	v_fmac_f32_dpp v229, v31, v151 row_shr:1 row_mask:0xf bank_mask:0xf bound_ctrl:1
	v_fmac_f32_dpp v230, v32, v152 row_shr:1 row_mask:0xf bank_mask:0xf bound_ctrl:1
	v_fmac_f32_dpp v231, v33, v153 row_shr:1 row_mask:0xf bank_mask:0xf bound_ctrl:1
	v_fmac_f32_dpp v224, v54, v130 row_shr:2 row_mask:0xf bank_mask:0xf bound_ctrl:1
	v_fmac_f32_dpp v225, v55, v131 row_shr:2 row_mask:0xf bank_mask:0xf bound_ctrl:1
	v_fmac_f32_dpp v226, v56, v132 row_shr:2 row_mask:0xf bank_mask:0xf bound_ctrl:1
	v_fmac_f32_dpp v227, v57, v133 row_shr:2 row_mask:0xf bank_mask:0xf bound_ctrl:1
	v_fmac_f32_dpp v228, v30, v146 row_shr:2 row_mask:0xf bank_mask:0xf bound_ctrl:1
	v_fmac_f32_dpp v229, v31, v147 row_shr:2 row_mask:0xf bank_mask:0xf bound_ctrl:1
	v_fmac_f32_dpp v230, v32, v148 row_shr:2 row_mask:0xf bank_mask:0xf bound_ctrl:1
	v_fmac_f32_dpp v231, v33, v149 row_shr:2 row_mask:0xf bank_mask:0xf bound_ctrl:1
	v_fmac_f32_dpp v224, v62, v134 row_shl:15 row_mask:0xf bank_mask:0xf bound_ctrl:1
	v_fmac_f32_dpp v225, v63, v135 row_shl:15 row_mask:0xf bank_mask:0xf bound_ctrl:1
	v_fmac_f32_dpp v226, v64, v136 row_shl:15 row_mask:0xf bank_mask:0xf bound_ctrl:1
	v_fmac_f32_dpp v227, v65, v137 row_shl:15 row_mask:0xf bank_mask:0xf bound_ctrl:1
	v_fmac_f32_dpp v228, v46, v150 row_shl:15 row_mask:0xf bank_mask:0xf bound_ctrl:1
	v_fmac_f32_dpp v229, v47, v151 row_shl:15 row_mask:0xf bank_mask:0xf bound_ctrl:1
	v_fmac_f32_dpp v230, v48, v152 row_shl:15 row_mask:0xf bank_mask:0xf bound_ctrl:1
	v_fmac_f32_dpp v231, v49, v153 row_shl:15 row_mask:0xf bank_mask:0xf bound_ctrl:1
	v_fmac_f32_dpp v224, v62, v130 row_shl:14 row_mask:0xf bank_mask:0xf bound_ctrl:1
	v_fmac_f32_dpp v225, v63, v131 row_shl:14 row_mask:0xf bank_mask:0xf bound_ctrl:1
	v_fmac_f32_dpp v226, v64, v132 row_shl:14 row_mask:0xf bank_mask:0xf bound_ctrl:1
	v_fmac_f32_dpp v227, v65, v133 row_shl:14 row_mask:0xf bank_mask:0xf bound_ctrl:1
	v_fmac_f32_dpp v228, v46, v146 row_shl:14 row_mask:0xf bank_mask:0xf bound_ctrl:1
	v_fmac_f32_dpp v229, v47, v147 row_shl:14 row_mask:0xf bank_mask:0xf bound_ctrl:1
	v_fmac_f32_dpp v230, v48, v148 row_shl:14 row_mask:0xf bank_mask:0xf bound_ctrl:1
	v_fmac_f32_dpp v231, v49, v149 row_shl:14 row_mask:0xf bank_mask:0xf bound_ctrl:1
	v_pk_mul_f32 v[232:233], v[224:225], s[48:49] op_sel_hi:[1,0]
	v_pk_mul_f32 v[234:235], v[226:227], s[48:49] op_sel_hi:[1,0]
	v_exp_f32_e32 v232, v232
	v_exp_f32_e32 v233, v233
	v_exp_f32_e32 v234, v234
	v_exp_f32_e32 v235, v235
	v_pk_add_f32 v[232:233], v[232:233], 1.0 op_sel_hi:[1,0]
	v_pk_add_f32 v[234:235], v[234:235], 1.0 op_sel_hi:[1,0]
	v_rcp_f32_e32 v232, v232
	v_rcp_f32_e32 v233, v233
	v_rcp_f32_e32 v234, v234
	v_rcp_f32_e32 v235, v235
	v_lshl_add_u64 v[220:221], v[220:221], 0, s[96:97]
	v_pk_mul_f32 v[224:225], v[224:225], v[232:233]
	v_pk_mul_f32 v[226:227], v[226:227], v[234:235]
	v_pk_mul_f32 v[224:225], v[224:225], v[228:229]
	v_pk_mul_f32 v[226:227], v[226:227], v[230:231]
	v_cvt_pk_bf16_f32 v168, v224, v225
	v_cvt_pk_bf16_f32 v169, v226, v227
	global_store_dwordx2 v[220:221], v[168:169], off
	v_pk_fma_f32 v[224:225], v[42:43], v[138:139], v[142:143]
	v_pk_fma_f32 v[226:227], v[44:45], v[140:141], v[144:145]
	v_pk_fma_f32 v[228:229], v[14:15], v[154:155], v[158:159]
	v_pk_fma_f32 v[230:231], v[16:17], v[156:157], v[160:161]
	v_fmac_f32_dpp v224, v42, v134 row_shr:1 row_mask:0xf bank_mask:0xf bound_ctrl:1
	v_fmac_f32_dpp v225, v43, v135 row_shr:1 row_mask:0xf bank_mask:0xf bound_ctrl:1
	v_fmac_f32_dpp v226, v44, v136 row_shr:1 row_mask:0xf bank_mask:0xf bound_ctrl:1
	v_fmac_f32_dpp v227, v45, v137 row_shr:1 row_mask:0xf bank_mask:0xf bound_ctrl:1
	v_fmac_f32_dpp v228, v14, v150 row_shr:1 row_mask:0xf bank_mask:0xf bound_ctrl:1
	v_fmac_f32_dpp v229, v15, v151 row_shr:1 row_mask:0xf bank_mask:0xf bound_ctrl:1
	v_fmac_f32_dpp v230, v16, v152 row_shr:1 row_mask:0xf bank_mask:0xf bound_ctrl:1
	v_fmac_f32_dpp v231, v17, v153 row_shr:1 row_mask:0xf bank_mask:0xf bound_ctrl:1
	v_fmac_f32_dpp v224, v42, v130 row_shr:2 row_mask:0xf bank_mask:0xf bound_ctrl:1
	v_fmac_f32_dpp v225, v43, v131 row_shr:2 row_mask:0xf bank_mask:0xf bound_ctrl:1
	v_fmac_f32_dpp v226, v44, v132 row_shr:2 row_mask:0xf bank_mask:0xf bound_ctrl:1
	v_fmac_f32_dpp v227, v45, v133 row_shr:2 row_mask:0xf bank_mask:0xf bound_ctrl:1
	v_fmac_f32_dpp v228, v14, v146 row_shr:2 row_mask:0xf bank_mask:0xf bound_ctrl:1
	v_fmac_f32_dpp v229, v15, v147 row_shr:2 row_mask:0xf bank_mask:0xf bound_ctrl:1
	v_fmac_f32_dpp v230, v16, v148 row_shr:2 row_mask:0xf bank_mask:0xf bound_ctrl:1
	v_fmac_f32_dpp v231, v17, v149 row_shr:2 row_mask:0xf bank_mask:0xf bound_ctrl:1
	v_fmac_f32_dpp v224, v54, v134 row_shl:15 row_mask:0xf bank_mask:0xf bound_ctrl:1
	v_fmac_f32_dpp v225, v55, v135 row_shl:15 row_mask:0xf bank_mask:0xf bound_ctrl:1
	v_fmac_f32_dpp v226, v56, v136 row_shl:15 row_mask:0xf bank_mask:0xf bound_ctrl:1
	v_fmac_f32_dpp v227, v57, v137 row_shl:15 row_mask:0xf bank_mask:0xf bound_ctrl:1
	v_fmac_f32_dpp v228, v30, v150 row_shl:15 row_mask:0xf bank_mask:0xf bound_ctrl:1
	v_fmac_f32_dpp v229, v31, v151 row_shl:15 row_mask:0xf bank_mask:0xf bound_ctrl:1
	v_fmac_f32_dpp v230, v32, v152 row_shl:15 row_mask:0xf bank_mask:0xf bound_ctrl:1
	v_fmac_f32_dpp v231, v33, v153 row_shl:15 row_mask:0xf bank_mask:0xf bound_ctrl:1
	v_fmac_f32_dpp v224, v54, v130 row_shl:14 row_mask:0xf bank_mask:0xf bound_ctrl:1
	v_fmac_f32_dpp v225, v55, v131 row_shl:14 row_mask:0xf bank_mask:0xf bound_ctrl:1
	v_fmac_f32_dpp v226, v56, v132 row_shl:14 row_mask:0xf bank_mask:0xf bound_ctrl:1
	v_fmac_f32_dpp v227, v57, v133 row_shl:14 row_mask:0xf bank_mask:0xf bound_ctrl:1
	v_fmac_f32_dpp v228, v30, v146 row_shl:14 row_mask:0xf bank_mask:0xf bound_ctrl:1
	v_fmac_f32_dpp v229, v31, v147 row_shl:14 row_mask:0xf bank_mask:0xf bound_ctrl:1
	v_fmac_f32_dpp v230, v32, v148 row_shl:14 row_mask:0xf bank_mask:0xf bound_ctrl:1
	v_fmac_f32_dpp v231, v33, v149 row_shl:14 row_mask:0xf bank_mask:0xf bound_ctrl:1
	v_pk_mul_f32 v[232:233], v[224:225], s[48:49] op_sel_hi:[1,0]
	v_pk_mul_f32 v[234:235], v[226:227], s[48:49] op_sel_hi:[1,0]
	v_exp_f32_e32 v232, v232
	v_exp_f32_e32 v233, v233
	v_exp_f32_e32 v234, v234
	v_exp_f32_e32 v235, v235
	v_pk_add_f32 v[232:233], v[232:233], 1.0 op_sel_hi:[1,0]
	v_pk_add_f32 v[234:235], v[234:235], 1.0 op_sel_hi:[1,0]
	v_rcp_f32_e32 v232, v232
	v_rcp_f32_e32 v233, v233
	v_rcp_f32_e32 v234, v234
	v_rcp_f32_e32 v235, v235
	v_lshl_add_u64 v[220:221], v[220:221], 0, s[96:97]
	v_pk_mul_f32 v[224:225], v[224:225], v[232:233]
	v_pk_mul_f32 v[226:227], v[226:227], v[234:235]
	v_pk_mul_f32 v[224:225], v[224:225], v[228:229]
	v_pk_mul_f32 v[226:227], v[226:227], v[230:231]
	v_cvt_pk_bf16_f32 v168, v224, v225
	v_cvt_pk_bf16_f32 v169, v226, v227
	global_store_dwordx2 v[220:221], v[168:169], off
	s_add_u32 s94, s26, s85
	s_addc_u32 s95, s27, 0
	v_lshl_add_u64 v[222:223], s[94:95], 0, v[216:217]
	v_lshl_add_u64 v[246:247], s[94:95], 0, v[218:219]
	s_and_saveexec_b64 s[46:47], s[6:7]
	global_store_dwordx4 v[222:223], v[26:29], off
	global_store_dwordx4 v[246:247], v[6:9], off
	s_or_b64 exec, exec, s[46:47]
	v_pk_fma_f32 v[224:225], v[26:27], v[138:139], v[142:143]
	v_pk_fma_f32 v[226:227], v[28:29], v[140:141], v[144:145]
	v_pk_fma_f32 v[228:229], v[6:7], v[154:155], v[158:159]
	v_pk_fma_f32 v[230:231], v[8:9], v[156:157], v[160:161]
	v_fmac_f32_dpp v224, v26, v134 row_shr:1 row_mask:0xf bank_mask:0xf bound_ctrl:1
	v_fmac_f32_dpp v225, v27, v135 row_shr:1 row_mask:0xf bank_mask:0xf bound_ctrl:1
	v_fmac_f32_dpp v226, v28, v136 row_shr:1 row_mask:0xf bank_mask:0xf bound_ctrl:1
	v_fmac_f32_dpp v227, v29, v137 row_shr:1 row_mask:0xf bank_mask:0xf bound_ctrl:1
	v_fmac_f32_dpp v228, v6, v150 row_shr:1 row_mask:0xf bank_mask:0xf bound_ctrl:1
	v_fmac_f32_dpp v229, v7, v151 row_shr:1 row_mask:0xf bank_mask:0xf bound_ctrl:1
	v_fmac_f32_dpp v230, v8, v152 row_shr:1 row_mask:0xf bank_mask:0xf bound_ctrl:1
	v_fmac_f32_dpp v231, v9, v153 row_shr:1 row_mask:0xf bank_mask:0xf bound_ctrl:1
	v_fmac_f32_dpp v224, v26, v130 row_shr:2 row_mask:0xf bank_mask:0xf bound_ctrl:1
	v_fmac_f32_dpp v225, v27, v131 row_shr:2 row_mask:0xf bank_mask:0xf bound_ctrl:1
	v_fmac_f32_dpp v226, v28, v132 row_shr:2 row_mask:0xf bank_mask:0xf bound_ctrl:1
	v_fmac_f32_dpp v227, v29, v133 row_shr:2 row_mask:0xf bank_mask:0xf bound_ctrl:1
	v_fmac_f32_dpp v228, v6, v146 row_shr:2 row_mask:0xf bank_mask:0xf bound_ctrl:1
	v_fmac_f32_dpp v229, v7, v147 row_shr:2 row_mask:0xf bank_mask:0xf bound_ctrl:1
	v_fmac_f32_dpp v230, v8, v148 row_shr:2 row_mask:0xf bank_mask:0xf bound_ctrl:1
	v_fmac_f32_dpp v231, v9, v149 row_shr:2 row_mask:0xf bank_mask:0xf bound_ctrl:1
	v_fmac_f32_dpp v224, v42, v134 row_shl:15 row_mask:0xf bank_mask:0xf bound_ctrl:1
	v_fmac_f32_dpp v225, v43, v135 row_shl:15 row_mask:0xf bank_mask:0xf bound_ctrl:1
	v_fmac_f32_dpp v226, v44, v136 row_shl:15 row_mask:0xf bank_mask:0xf bound_ctrl:1
	v_fmac_f32_dpp v227, v45, v137 row_shl:15 row_mask:0xf bank_mask:0xf bound_ctrl:1
	v_fmac_f32_dpp v228, v14, v150 row_shl:15 row_mask:0xf bank_mask:0xf bound_ctrl:1
	v_fmac_f32_dpp v229, v15, v151 row_shl:15 row_mask:0xf bank_mask:0xf bound_ctrl:1
	v_fmac_f32_dpp v230, v16, v152 row_shl:15 row_mask:0xf bank_mask:0xf bound_ctrl:1
	v_fmac_f32_dpp v231, v17, v153 row_shl:15 row_mask:0xf bank_mask:0xf bound_ctrl:1
	v_fmac_f32_dpp v224, v42, v130 row_shl:14 row_mask:0xf bank_mask:0xf bound_ctrl:1
	v_fmac_f32_dpp v225, v43, v131 row_shl:14 row_mask:0xf bank_mask:0xf bound_ctrl:1
	v_fmac_f32_dpp v226, v44, v132 row_shl:14 row_mask:0xf bank_mask:0xf bound_ctrl:1
	v_fmac_f32_dpp v227, v45, v133 row_shl:14 row_mask:0xf bank_mask:0xf bound_ctrl:1
	v_fmac_f32_dpp v228, v14, v146 row_shl:14 row_mask:0xf bank_mask:0xf bound_ctrl:1
	v_fmac_f32_dpp v229, v15, v147 row_shl:14 row_mask:0xf bank_mask:0xf bound_ctrl:1
	v_fmac_f32_dpp v230, v16, v148 row_shl:14 row_mask:0xf bank_mask:0xf bound_ctrl:1
	v_fmac_f32_dpp v231, v17, v149 row_shl:14 row_mask:0xf bank_mask:0xf bound_ctrl:1
	v_pk_mul_f32 v[232:233], v[224:225], s[48:49] op_sel_hi:[1,0]
	v_pk_mul_f32 v[234:235], v[226:227], s[48:49] op_sel_hi:[1,0]
	v_exp_f32_e32 v232, v232
	v_exp_f32_e32 v233, v233
	v_exp_f32_e32 v234, v234
	v_exp_f32_e32 v235, v235
	v_pk_add_f32 v[232:233], v[232:233], 1.0 op_sel_hi:[1,0]
	v_pk_add_f32 v[234:235], v[234:235], 1.0 op_sel_hi:[1,0]
	v_rcp_f32_e32 v232, v232
	v_rcp_f32_e32 v233, v233
	v_rcp_f32_e32 v234, v234
	v_rcp_f32_e32 v235, v235
	v_lshl_add_u64 v[220:221], v[220:221], 0, s[96:97]
	v_pk_mul_f32 v[224:225], v[224:225], v[232:233]
	v_pk_mul_f32 v[226:227], v[226:227], v[234:235]
	v_pk_mul_f32 v[224:225], v[224:225], v[228:229]
	v_pk_mul_f32 v[226:227], v[226:227], v[230:231]
	v_cvt_pk_bf16_f32 v168, v224, v225
	v_cvt_pk_bf16_f32 v169, v226, v227
	global_store_dwordx2 v[220:221], v[168:169], off
	s_waitcnt lgkmcnt(0)
	s_add_i32 s84, s39, 0
	s_mul_i32 s85, s84, 0xb0000
	s_add_u32 s94, s22, s85
	s_addc_u32 s95, s23, 0
	v_lshl_add_u64 v[220:221], s[94:95], 0, v[210:211]
	s_mul_i32 s85, s84, 0x16000
	s_add_u32 s94, s24, s85
	s_addc_u32 s95, s25, 0
	v_lshl_add_u64 v[222:223], s[94:95], 0, v[212:213]
	v_lshl_add_u64 v[246:247], s[94:95], 0, v[214:215]
	s_and_saveexec_b64 s[46:47], s[4:5]
	global_store_dwordx4 v[222:223], v[122:125], off offset:64
	global_store_dwordx4 v[246:247], v[102:105], off offset:64
	s_or_b64 exec, exec, s[46:47]
	v_pk_fma_f32 v[224:225], v[122:123], v[186:187], v[190:191]
	v_pk_fma_f32 v[226:227], v[124:125], v[188:189], v[192:193]
	v_pk_fma_f32 v[228:229], v[102:103], v[202:203], v[206:207]
	v_pk_fma_f32 v[230:231], v[104:105], v[204:205], v[208:209]
	v_fmac_f32_dpp v224, v122, v182 row_shr:1 row_mask:0xf bank_mask:0xf bound_ctrl:1
	v_fmac_f32_dpp v225, v123, v183 row_shr:1 row_mask:0xf bank_mask:0xf bound_ctrl:1
	v_fmac_f32_dpp v226, v124, v184 row_shr:1 row_mask:0xf bank_mask:0xf bound_ctrl:1
	v_fmac_f32_dpp v227, v125, v185 row_shr:1 row_mask:0xf bank_mask:0xf bound_ctrl:1
	v_fmac_f32_dpp v228, v102, v198 row_shr:1 row_mask:0xf bank_mask:0xf bound_ctrl:1
	v_fmac_f32_dpp v229, v103, v199 row_shr:1 row_mask:0xf bank_mask:0xf bound_ctrl:1
	v_fmac_f32_dpp v230, v104, v200 row_shr:1 row_mask:0xf bank_mask:0xf bound_ctrl:1
	v_fmac_f32_dpp v231, v105, v201 row_shr:1 row_mask:0xf bank_mask:0xf bound_ctrl:1
	v_fmac_f32_dpp v224, v122, v178 row_shr:2 row_mask:0xf bank_mask:0xf bound_ctrl:1
	v_fmac_f32_dpp v225, v123, v179 row_shr:2 row_mask:0xf bank_mask:0xf bound_ctrl:1
	v_fmac_f32_dpp v226, v124, v180 row_shr:2 row_mask:0xf bank_mask:0xf bound_ctrl:1
	v_fmac_f32_dpp v227, v125, v181 row_shr:2 row_mask:0xf bank_mask:0xf bound_ctrl:1
	v_fmac_f32_dpp v228, v102, v194 row_shr:2 row_mask:0xf bank_mask:0xf bound_ctrl:1
	v_fmac_f32_dpp v229, v103, v195 row_shr:2 row_mask:0xf bank_mask:0xf bound_ctrl:1
	v_fmac_f32_dpp v230, v104, v196 row_shr:2 row_mask:0xf bank_mask:0xf bound_ctrl:1
	v_fmac_f32_dpp v231, v105, v197 row_shr:2 row_mask:0xf bank_mask:0xf bound_ctrl:1
	v_pk_mul_f32 v[232:233], v[224:225], s[48:49] op_sel_hi:[1,0]
	v_pk_mul_f32 v[234:235], v[226:227], s[48:49] op_sel_hi:[1,0]
	v_exp_f32_e32 v232, v232
	v_exp_f32_e32 v233, v233
	v_exp_f32_e32 v234, v234
	v_exp_f32_e32 v235, v235
	v_pk_add_f32 v[232:233], v[232:233], 1.0 op_sel_hi:[1,0]
	v_pk_add_f32 v[234:235], v[234:235], 1.0 op_sel_hi:[1,0]
	v_rcp_f32_e32 v232, v232
	v_rcp_f32_e32 v233, v233
	v_rcp_f32_e32 v234, v234
	v_rcp_f32_e32 v235, v235
	v_pk_mul_f32 v[224:225], v[224:225], v[232:233]
	v_pk_mul_f32 v[226:227], v[226:227], v[234:235]
	v_pk_mul_f32 v[224:225], v[224:225], v[228:229]
	v_pk_mul_f32 v[226:227], v[226:227], v[230:231]
	v_cvt_pk_bf16_f32 v168, v224, v225
	v_cvt_pk_bf16_f32 v169, v226, v227
	s_and_saveexec_b64 s[46:47], s[8:9]
	global_store_dwordx2 v[220:221], v[168:169], off offset:32
	s_or_b64 exec, exec, s[46:47]
	v_pk_fma_f32 v[224:225], v[114:115], v[186:187], v[190:191]
	v_pk_fma_f32 v[226:227], v[116:117], v[188:189], v[192:193]
	v_pk_fma_f32 v[228:229], v[86:87], v[202:203], v[206:207]
	v_pk_fma_f32 v[230:231], v[88:89], v[204:205], v[208:209]
	v_fmac_f32_dpp v224, v114, v182 row_shr:1 row_mask:0xf bank_mask:0xf bound_ctrl:1
	v_fmac_f32_dpp v225, v115, v183 row_shr:1 row_mask:0xf bank_mask:0xf bound_ctrl:1
	v_fmac_f32_dpp v226, v116, v184 row_shr:1 row_mask:0xf bank_mask:0xf bound_ctrl:1
	v_fmac_f32_dpp v227, v117, v185 row_shr:1 row_mask:0xf bank_mask:0xf bound_ctrl:1
	v_fmac_f32_dpp v228, v86, v198 row_shr:1 row_mask:0xf bank_mask:0xf bound_ctrl:1
	v_fmac_f32_dpp v229, v87, v199 row_shr:1 row_mask:0xf bank_mask:0xf bound_ctrl:1
	v_fmac_f32_dpp v230, v88, v200 row_shr:1 row_mask:0xf bank_mask:0xf bound_ctrl:1
	v_fmac_f32_dpp v231, v89, v201 row_shr:1 row_mask:0xf bank_mask:0xf bound_ctrl:1
	v_fmac_f32_dpp v224, v114, v178 row_shr:2 row_mask:0xf bank_mask:0xf bound_ctrl:1
	v_fmac_f32_dpp v225, v115, v179 row_shr:2 row_mask:0xf bank_mask:0xf bound_ctrl:1
	v_fmac_f32_dpp v226, v116, v180 row_shr:2 row_mask:0xf bank_mask:0xf bound_ctrl:1
	v_fmac_f32_dpp v227, v117, v181 row_shr:2 row_mask:0xf bank_mask:0xf bound_ctrl:1
	v_fmac_f32_dpp v228, v86, v194 row_shr:2 row_mask:0xf bank_mask:0xf bound_ctrl:1
	v_fmac_f32_dpp v229, v87, v195 row_shr:2 row_mask:0xf bank_mask:0xf bound_ctrl:1
	v_fmac_f32_dpp v230, v88, v196 row_shr:2 row_mask:0xf bank_mask:0xf bound_ctrl:1
	v_fmac_f32_dpp v231, v89, v197 row_shr:2 row_mask:0xf bank_mask:0xf bound_ctrl:1
	v_fmac_f32_dpp v224, v122, v182 row_shl:15 row_mask:0xf bank_mask:0xf bound_ctrl:1
	v_fmac_f32_dpp v225, v123, v183 row_shl:15 row_mask:0xf bank_mask:0xf bound_ctrl:1
	v_fmac_f32_dpp v226, v124, v184 row_shl:15 row_mask:0xf bank_mask:0xf bound_ctrl:1
	v_fmac_f32_dpp v227, v125, v185 row_shl:15 row_mask:0xf bank_mask:0xf bound_ctrl:1
	v_fmac_f32_dpp v228, v102, v198 row_shl:15 row_mask:0xf bank_mask:0xf bound_ctrl:1
	v_fmac_f32_dpp v229, v103, v199 row_shl:15 row_mask:0xf bank_mask:0xf bound_ctrl:1
	v_fmac_f32_dpp v230, v104, v200 row_shl:15 row_mask:0xf bank_mask:0xf bound_ctrl:1
	v_fmac_f32_dpp v231, v105, v201 row_shl:15 row_mask:0xf bank_mask:0xf bound_ctrl:1
	v_fmac_f32_dpp v224, v122, v178 row_shl:14 row_mask:0xf bank_mask:0xf bound_ctrl:1
	v_fmac_f32_dpp v225, v123, v179 row_shl:14 row_mask:0xf bank_mask:0xf bound_ctrl:1
	v_fmac_f32_dpp v226, v124, v180 row_shl:14 row_mask:0xf bank_mask:0xf bound_ctrl:1
	v_fmac_f32_dpp v227, v125, v181 row_shl:14 row_mask:0xf bank_mask:0xf bound_ctrl:1
	v_fmac_f32_dpp v228, v102, v194 row_shl:14 row_mask:0xf bank_mask:0xf bound_ctrl:1
	v_fmac_f32_dpp v229, v103, v195 row_shl:14 row_mask:0xf bank_mask:0xf bound_ctrl:1
	v_fmac_f32_dpp v230, v104, v196 row_shl:14 row_mask:0xf bank_mask:0xf bound_ctrl:1
	v_fmac_f32_dpp v231, v105, v197 row_shl:14 row_mask:0xf bank_mask:0xf bound_ctrl:1
	v_pk_mul_f32 v[232:233], v[224:225], s[48:49] op_sel_hi:[1,0]
	v_pk_mul_f32 v[234:235], v[226:227], s[48:49] op_sel_hi:[1,0]
	v_exp_f32_e32 v232, v232
	v_exp_f32_e32 v233, v233
	v_exp_f32_e32 v234, v234
	v_exp_f32_e32 v235, v235
	v_pk_add_f32 v[232:233], v[232:233], 1.0 op_sel_hi:[1,0]
	v_pk_add_f32 v[234:235], v[234:235], 1.0 op_sel_hi:[1,0]
	v_rcp_f32_e32 v232, v232
	v_rcp_f32_e32 v233, v233
	v_rcp_f32_e32 v234, v234
	v_rcp_f32_e32 v235, v235
	v_lshl_add_u64 v[220:221], v[220:221], 0, s[96:97]
	v_pk_mul_f32 v[224:225], v[224:225], v[232:233]
	v_pk_mul_f32 v[226:227], v[226:227], v[234:235]
	v_pk_mul_f32 v[224:225], v[224:225], v[228:229]
	v_pk_mul_f32 v[226:227], v[226:227], v[230:231]
	v_cvt_pk_bf16_f32 v168, v224, v225
	v_cvt_pk_bf16_f32 v169, v226, v227
	global_store_dwordx2 v[220:221], v[168:169], off offset:32
	v_pk_fma_f32 v[224:225], v[98:99], v[186:187], v[190:191]
	v_pk_fma_f32 v[226:227], v[100:101], v[188:189], v[192:193]
	v_pk_fma_f32 v[228:229], v[74:75], v[202:203], v[206:207]
	v_pk_fma_f32 v[230:231], v[76:77], v[204:205], v[208:209]
	v_fmac_f32_dpp v224, v98, v182 row_shr:1 row_mask:0xf bank_mask:0xf bound_ctrl:1
	v_fmac_f32_dpp v225, v99, v183 row_shr:1 row_mask:0xf bank_mask:0xf bound_ctrl:1
	v_fmac_f32_dpp v226, v100, v184 row_shr:1 row_mask:0xf bank_mask:0xf bound_ctrl:1
	v_fmac_f32_dpp v227, v101, v185 row_shr:1 row_mask:0xf bank_mask:0xf bound_ctrl:1
	v_fmac_f32_dpp v228, v74, v198 row_shr:1 row_mask:0xf bank_mask:0xf bound_ctrl:1
	v_fmac_f32_dpp v229, v75, v199 row_shr:1 row_mask:0xf bank_mask:0xf bound_ctrl:1
	v_fmac_f32_dpp v230, v76, v200 row_shr:1 row_mask:0xf bank_mask:0xf bound_ctrl:1
	v_fmac_f32_dpp v231, v77, v201 row_shr:1 row_mask:0xf bank_mask:0xf bound_ctrl:1
	v_fmac_f32_dpp v224, v98, v178 row_shr:2 row_mask:0xf bank_mask:0xf bound_ctrl:1
	v_fmac_f32_dpp v225, v99, v179 row_shr:2 row_mask:0xf bank_mask:0xf bound_ctrl:1
	v_fmac_f32_dpp v226, v100, v180 row_shr:2 row_mask:0xf bank_mask:0xf bound_ctrl:1
	v_fmac_f32_dpp v227, v101, v181 row_shr:2 row_mask:0xf bank_mask:0xf bound_ctrl:1
	v_fmac_f32_dpp v228, v74, v194 row_shr:2 row_mask:0xf bank_mask:0xf bound_ctrl:1
	v_fmac_f32_dpp v229, v75, v195 row_shr:2 row_mask:0xf bank_mask:0xf bound_ctrl:1
	v_fmac_f32_dpp v230, v76, v196 row_shr:2 row_mask:0xf bank_mask:0xf bound_ctrl:1
	v_fmac_f32_dpp v231, v77, v197 row_shr:2 row_mask:0xf bank_mask:0xf bound_ctrl:1
	v_fmac_f32_dpp v224, v114, v182 row_shl:15 row_mask:0xf bank_mask:0xf bound_ctrl:1
	v_fmac_f32_dpp v225, v115, v183 row_shl:15 row_mask:0xf bank_mask:0xf bound_ctrl:1
	v_fmac_f32_dpp v226, v116, v184 row_shl:15 row_mask:0xf bank_mask:0xf bound_ctrl:1
	v_fmac_f32_dpp v227, v117, v185 row_shl:15 row_mask:0xf bank_mask:0xf bound_ctrl:1
	v_fmac_f32_dpp v228, v86, v198 row_shl:15 row_mask:0xf bank_mask:0xf bound_ctrl:1
	v_fmac_f32_dpp v229, v87, v199 row_shl:15 row_mask:0xf bank_mask:0xf bound_ctrl:1
	v_fmac_f32_dpp v230, v88, v200 row_shl:15 row_mask:0xf bank_mask:0xf bound_ctrl:1
	v_fmac_f32_dpp v231, v89, v201 row_shl:15 row_mask:0xf bank_mask:0xf bound_ctrl:1
	v_fmac_f32_dpp v224, v114, v178 row_shl:14 row_mask:0xf bank_mask:0xf bound_ctrl:1
	v_fmac_f32_dpp v225, v115, v179 row_shl:14 row_mask:0xf bank_mask:0xf bound_ctrl:1
	v_fmac_f32_dpp v226, v116, v180 row_shl:14 row_mask:0xf bank_mask:0xf bound_ctrl:1
	v_fmac_f32_dpp v227, v117, v181 row_shl:14 row_mask:0xf bank_mask:0xf bound_ctrl:1
	v_fmac_f32_dpp v228, v86, v194 row_shl:14 row_mask:0xf bank_mask:0xf bound_ctrl:1
	v_fmac_f32_dpp v229, v87, v195 row_shl:14 row_mask:0xf bank_mask:0xf bound_ctrl:1
	v_fmac_f32_dpp v230, v88, v196 row_shl:14 row_mask:0xf bank_mask:0xf bound_ctrl:1
	v_fmac_f32_dpp v231, v89, v197 row_shl:14 row_mask:0xf bank_mask:0xf bound_ctrl:1
	v_pk_mul_f32 v[232:233], v[224:225], s[48:49] op_sel_hi:[1,0]
	v_pk_mul_f32 v[234:235], v[226:227], s[48:49] op_sel_hi:[1,0]
	v_exp_f32_e32 v232, v232
	v_exp_f32_e32 v233, v233
	v_exp_f32_e32 v234, v234
	v_exp_f32_e32 v235, v235
	v_pk_add_f32 v[232:233], v[232:233], 1.0 op_sel_hi:[1,0]
	v_pk_add_f32 v[234:235], v[234:235], 1.0 op_sel_hi:[1,0]
	v_rcp_f32_e32 v232, v232
	v_rcp_f32_e32 v233, v233
	v_rcp_f32_e32 v234, v234
	v_rcp_f32_e32 v235, v235
	v_lshl_add_u64 v[220:221], v[220:221], 0, s[96:97]
	v_pk_mul_f32 v[224:225], v[224:225], v[232:233]
	v_pk_mul_f32 v[226:227], v[226:227], v[234:235]
	v_pk_mul_f32 v[224:225], v[224:225], v[228:229]
	v_pk_mul_f32 v[226:227], v[226:227], v[230:231]
	v_cvt_pk_bf16_f32 v168, v224, v225
	v_cvt_pk_bf16_f32 v169, v226, v227
	global_store_dwordx2 v[220:221], v[168:169], off offset:32
	s_add_u32 s94, s26, s85
	s_addc_u32 s95, s27, 0
	v_lshl_add_u64 v[222:223], s[94:95], 0, v[216:217]
	v_lshl_add_u64 v[246:247], s[94:95], 0, v[218:219]
	s_and_saveexec_b64 s[46:47], s[6:7]
	global_store_dwordx4 v[222:223], v[82:85], off offset:64
	global_store_dwordx4 v[246:247], v[66:69], off offset:64
	s_or_b64 exec, exec, s[46:47]
	v_pk_fma_f32 v[224:225], v[82:83], v[186:187], v[190:191]
	v_pk_fma_f32 v[226:227], v[84:85], v[188:189], v[192:193]
	v_pk_fma_f32 v[228:229], v[66:67], v[202:203], v[206:207]
	v_pk_fma_f32 v[230:231], v[68:69], v[204:205], v[208:209]
	v_fmac_f32_dpp v224, v82, v182 row_shr:1 row_mask:0xf bank_mask:0xf bound_ctrl:1
	v_fmac_f32_dpp v225, v83, v183 row_shr:1 row_mask:0xf bank_mask:0xf bound_ctrl:1
	v_fmac_f32_dpp v226, v84, v184 row_shr:1 row_mask:0xf bank_mask:0xf bound_ctrl:1
	v_fmac_f32_dpp v227, v85, v185 row_shr:1 row_mask:0xf bank_mask:0xf bound_ctrl:1
	v_fmac_f32_dpp v228, v66, v198 row_shr:1 row_mask:0xf bank_mask:0xf bound_ctrl:1
	v_fmac_f32_dpp v229, v67, v199 row_shr:1 row_mask:0xf bank_mask:0xf bound_ctrl:1
	v_fmac_f32_dpp v230, v68, v200 row_shr:1 row_mask:0xf bank_mask:0xf bound_ctrl:1
	v_fmac_f32_dpp v231, v69, v201 row_shr:1 row_mask:0xf bank_mask:0xf bound_ctrl:1
	v_fmac_f32_dpp v224, v82, v178 row_shr:2 row_mask:0xf bank_mask:0xf bound_ctrl:1
	v_fmac_f32_dpp v225, v83, v179 row_shr:2 row_mask:0xf bank_mask:0xf bound_ctrl:1
	v_fmac_f32_dpp v226, v84, v180 row_shr:2 row_mask:0xf bank_mask:0xf bound_ctrl:1
	v_fmac_f32_dpp v227, v85, v181 row_shr:2 row_mask:0xf bank_mask:0xf bound_ctrl:1
	v_fmac_f32_dpp v228, v66, v194 row_shr:2 row_mask:0xf bank_mask:0xf bound_ctrl:1
	v_fmac_f32_dpp v229, v67, v195 row_shr:2 row_mask:0xf bank_mask:0xf bound_ctrl:1
	v_fmac_f32_dpp v230, v68, v196 row_shr:2 row_mask:0xf bank_mask:0xf bound_ctrl:1
	v_fmac_f32_dpp v231, v69, v197 row_shr:2 row_mask:0xf bank_mask:0xf bound_ctrl:1
	v_fmac_f32_dpp v224, v98, v182 row_shl:15 row_mask:0xf bank_mask:0xf bound_ctrl:1
	v_fmac_f32_dpp v225, v99, v183 row_shl:15 row_mask:0xf bank_mask:0xf bound_ctrl:1
	v_fmac_f32_dpp v226, v100, v184 row_shl:15 row_mask:0xf bank_mask:0xf bound_ctrl:1
	v_fmac_f32_dpp v227, v101, v185 row_shl:15 row_mask:0xf bank_mask:0xf bound_ctrl:1
	v_fmac_f32_dpp v228, v74, v198 row_shl:15 row_mask:0xf bank_mask:0xf bound_ctrl:1
	v_fmac_f32_dpp v229, v75, v199 row_shl:15 row_mask:0xf bank_mask:0xf bound_ctrl:1
	v_fmac_f32_dpp v230, v76, v200 row_shl:15 row_mask:0xf bank_mask:0xf bound_ctrl:1
	v_fmac_f32_dpp v231, v77, v201 row_shl:15 row_mask:0xf bank_mask:0xf bound_ctrl:1
	v_fmac_f32_dpp v224, v98, v178 row_shl:14 row_mask:0xf bank_mask:0xf bound_ctrl:1
	v_fmac_f32_dpp v225, v99, v179 row_shl:14 row_mask:0xf bank_mask:0xf bound_ctrl:1
	v_fmac_f32_dpp v226, v100, v180 row_shl:14 row_mask:0xf bank_mask:0xf bound_ctrl:1
	v_fmac_f32_dpp v227, v101, v181 row_shl:14 row_mask:0xf bank_mask:0xf bound_ctrl:1
	v_fmac_f32_dpp v228, v74, v194 row_shl:14 row_mask:0xf bank_mask:0xf bound_ctrl:1
	v_fmac_f32_dpp v229, v75, v195 row_shl:14 row_mask:0xf bank_mask:0xf bound_ctrl:1
	v_fmac_f32_dpp v230, v76, v196 row_shl:14 row_mask:0xf bank_mask:0xf bound_ctrl:1
	v_fmac_f32_dpp v231, v77, v197 row_shl:14 row_mask:0xf bank_mask:0xf bound_ctrl:1
	v_pk_mul_f32 v[232:233], v[224:225], s[48:49] op_sel_hi:[1,0]
	v_pk_mul_f32 v[234:235], v[226:227], s[48:49] op_sel_hi:[1,0]
	v_exp_f32_e32 v232, v232
	v_exp_f32_e32 v233, v233
	v_exp_f32_e32 v234, v234
	v_exp_f32_e32 v235, v235
	v_pk_add_f32 v[232:233], v[232:233], 1.0 op_sel_hi:[1,0]
	v_pk_add_f32 v[234:235], v[234:235], 1.0 op_sel_hi:[1,0]
	v_rcp_f32_e32 v232, v232
	v_rcp_f32_e32 v233, v233
	v_rcp_f32_e32 v234, v234
	v_rcp_f32_e32 v235, v235
	v_lshl_add_u64 v[220:221], v[220:221], 0, s[96:97]
	v_pk_mul_f32 v[224:225], v[224:225], v[232:233]
	v_pk_mul_f32 v[226:227], v[226:227], v[234:235]
	v_pk_mul_f32 v[224:225], v[224:225], v[228:229]
	v_pk_mul_f32 v[226:227], v[226:227], v[230:231]
	v_cvt_pk_bf16_f32 v168, v224, v225
	v_cvt_pk_bf16_f32 v169, v226, v227
	global_store_dwordx2 v[220:221], v[168:169], off offset:32
	s_add_i32 s84, s39, 2
	s_mul_i32 s85, s84, 0xb0000
	s_add_u32 s94, s22, s85
	s_addc_u32 s95, s23, 0
	v_lshl_add_u64 v[220:221], s[94:95], 0, v[210:211]
	s_mul_i32 s85, s84, 0x16000
	s_add_u32 s94, s24, s85
	s_addc_u32 s95, s25, 0
	v_lshl_add_u64 v[222:223], s[94:95], 0, v[212:213]
	v_lshl_add_u64 v[246:247], s[94:95], 0, v[214:215]
	s_and_saveexec_b64 s[46:47], s[4:5]
	global_store_dwordx4 v[222:223], v[58:61], off offset:64
	global_store_dwordx4 v[246:247], v[38:41], off offset:64
	s_or_b64 exec, exec, s[46:47]
	v_pk_fma_f32 v[224:225], v[58:59], v[186:187], v[190:191]
	v_pk_fma_f32 v[226:227], v[60:61], v[188:189], v[192:193]
	v_pk_fma_f32 v[228:229], v[38:39], v[202:203], v[206:207]
	v_pk_fma_f32 v[230:231], v[40:41], v[204:205], v[208:209]
	v_fmac_f32_dpp v224, v58, v182 row_shr:1 row_mask:0xf bank_mask:0xf bound_ctrl:1
	v_fmac_f32_dpp v225, v59, v183 row_shr:1 row_mask:0xf bank_mask:0xf bound_ctrl:1
	v_fmac_f32_dpp v226, v60, v184 row_shr:1 row_mask:0xf bank_mask:0xf bound_ctrl:1
	v_fmac_f32_dpp v227, v61, v185 row_shr:1 row_mask:0xf bank_mask:0xf bound_ctrl:1
	v_fmac_f32_dpp v228, v38, v198 row_shr:1 row_mask:0xf bank_mask:0xf bound_ctrl:1
	v_fmac_f32_dpp v229, v39, v199 row_shr:1 row_mask:0xf bank_mask:0xf bound_ctrl:1
	v_fmac_f32_dpp v230, v40, v200 row_shr:1 row_mask:0xf bank_mask:0xf bound_ctrl:1
	v_fmac_f32_dpp v231, v41, v201 row_shr:1 row_mask:0xf bank_mask:0xf bound_ctrl:1
	v_fmac_f32_dpp v224, v58, v178 row_shr:2 row_mask:0xf bank_mask:0xf bound_ctrl:1
	v_fmac_f32_dpp v225, v59, v179 row_shr:2 row_mask:0xf bank_mask:0xf bound_ctrl:1
	v_fmac_f32_dpp v226, v60, v180 row_shr:2 row_mask:0xf bank_mask:0xf bound_ctrl:1
	v_fmac_f32_dpp v227, v61, v181 row_shr:2 row_mask:0xf bank_mask:0xf bound_ctrl:1
	v_fmac_f32_dpp v228, v38, v194 row_shr:2 row_mask:0xf bank_mask:0xf bound_ctrl:1
	v_fmac_f32_dpp v229, v39, v195 row_shr:2 row_mask:0xf bank_mask:0xf bound_ctrl:1
	v_fmac_f32_dpp v230, v40, v196 row_shr:2 row_mask:0xf bank_mask:0xf bound_ctrl:1
	v_fmac_f32_dpp v231, v41, v197 row_shr:2 row_mask:0xf bank_mask:0xf bound_ctrl:1
	v_pk_mul_f32 v[232:233], v[224:225], s[48:49] op_sel_hi:[1,0]
	v_pk_mul_f32 v[234:235], v[226:227], s[48:49] op_sel_hi:[1,0]
	v_exp_f32_e32 v232, v232
	v_exp_f32_e32 v233, v233
	v_exp_f32_e32 v234, v234
	v_exp_f32_e32 v235, v235
	v_pk_add_f32 v[232:233], v[232:233], 1.0 op_sel_hi:[1,0]
	v_pk_add_f32 v[234:235], v[234:235], 1.0 op_sel_hi:[1,0]
	v_rcp_f32_e32 v232, v232
	v_rcp_f32_e32 v233, v233
	v_rcp_f32_e32 v234, v234
	v_rcp_f32_e32 v235, v235
	v_pk_mul_f32 v[224:225], v[224:225], v[232:233]
	v_pk_mul_f32 v[226:227], v[226:227], v[234:235]
	v_pk_mul_f32 v[224:225], v[224:225], v[228:229]
	v_pk_mul_f32 v[226:227], v[226:227], v[230:231]
	v_cvt_pk_bf16_f32 v168, v224, v225
	v_cvt_pk_bf16_f32 v169, v226, v227
	s_and_saveexec_b64 s[46:47], s[8:9]
	global_store_dwordx2 v[220:221], v[168:169], off offset:32
	s_or_b64 exec, exec, s[46:47]
	v_pk_fma_f32 v[224:225], v[50:51], v[186:187], v[190:191]
	v_pk_fma_f32 v[226:227], v[52:53], v[188:189], v[192:193]
	v_pk_fma_f32 v[228:229], v[22:23], v[202:203], v[206:207]
	v_pk_fma_f32 v[230:231], v[24:25], v[204:205], v[208:209]
	v_fmac_f32_dpp v224, v50, v182 row_shr:1 row_mask:0xf bank_mask:0xf bound_ctrl:1
	v_fmac_f32_dpp v225, v51, v183 row_shr:1 row_mask:0xf bank_mask:0xf bound_ctrl:1
	v_fmac_f32_dpp v226, v52, v184 row_shr:1 row_mask:0xf bank_mask:0xf bound_ctrl:1
	v_fmac_f32_dpp v227, v53, v185 row_shr:1 row_mask:0xf bank_mask:0xf bound_ctrl:1
	v_fmac_f32_dpp v228, v22, v198 row_shr:1 row_mask:0xf bank_mask:0xf bound_ctrl:1
	v_fmac_f32_dpp v229, v23, v199 row_shr:1 row_mask:0xf bank_mask:0xf bound_ctrl:1
	v_fmac_f32_dpp v230, v24, v200 row_shr:1 row_mask:0xf bank_mask:0xf bound_ctrl:1
	v_fmac_f32_dpp v231, v25, v201 row_shr:1 row_mask:0xf bank_mask:0xf bound_ctrl:1
	v_fmac_f32_dpp v224, v50, v178 row_shr:2 row_mask:0xf bank_mask:0xf bound_ctrl:1
	v_fmac_f32_dpp v225, v51, v179 row_shr:2 row_mask:0xf bank_mask:0xf bound_ctrl:1
	v_fmac_f32_dpp v226, v52, v180 row_shr:2 row_mask:0xf bank_mask:0xf bound_ctrl:1
	v_fmac_f32_dpp v227, v53, v181 row_shr:2 row_mask:0xf bank_mask:0xf bound_ctrl:1
	v_fmac_f32_dpp v228, v22, v194 row_shr:2 row_mask:0xf bank_mask:0xf bound_ctrl:1
	v_fmac_f32_dpp v229, v23, v195 row_shr:2 row_mask:0xf bank_mask:0xf bound_ctrl:1
	v_fmac_f32_dpp v230, v24, v196 row_shr:2 row_mask:0xf bank_mask:0xf bound_ctrl:1
	v_fmac_f32_dpp v231, v25, v197 row_shr:2 row_mask:0xf bank_mask:0xf bound_ctrl:1
	v_fmac_f32_dpp v224, v58, v182 row_shl:15 row_mask:0xf bank_mask:0xf bound_ctrl:1
	v_fmac_f32_dpp v225, v59, v183 row_shl:15 row_mask:0xf bank_mask:0xf bound_ctrl:1
	v_fmac_f32_dpp v226, v60, v184 row_shl:15 row_mask:0xf bank_mask:0xf bound_ctrl:1
	v_fmac_f32_dpp v227, v61, v185 row_shl:15 row_mask:0xf bank_mask:0xf bound_ctrl:1
	v_fmac_f32_dpp v228, v38, v198 row_shl:15 row_mask:0xf bank_mask:0xf bound_ctrl:1
	v_fmac_f32_dpp v229, v39, v199 row_shl:15 row_mask:0xf bank_mask:0xf bound_ctrl:1
	v_fmac_f32_dpp v230, v40, v200 row_shl:15 row_mask:0xf bank_mask:0xf bound_ctrl:1
	v_fmac_f32_dpp v231, v41, v201 row_shl:15 row_mask:0xf bank_mask:0xf bound_ctrl:1
	v_fmac_f32_dpp v224, v58, v178 row_shl:14 row_mask:0xf bank_mask:0xf bound_ctrl:1
	v_fmac_f32_dpp v225, v59, v179 row_shl:14 row_mask:0xf bank_mask:0xf bound_ctrl:1
	v_fmac_f32_dpp v226, v60, v180 row_shl:14 row_mask:0xf bank_mask:0xf bound_ctrl:1
	v_fmac_f32_dpp v227, v61, v181 row_shl:14 row_mask:0xf bank_mask:0xf bound_ctrl:1
	v_fmac_f32_dpp v228, v38, v194 row_shl:14 row_mask:0xf bank_mask:0xf bound_ctrl:1
	v_fmac_f32_dpp v229, v39, v195 row_shl:14 row_mask:0xf bank_mask:0xf bound_ctrl:1
	v_fmac_f32_dpp v230, v40, v196 row_shl:14 row_mask:0xf bank_mask:0xf bound_ctrl:1
	v_fmac_f32_dpp v231, v41, v197 row_shl:14 row_mask:0xf bank_mask:0xf bound_ctrl:1
	v_pk_mul_f32 v[232:233], v[224:225], s[48:49] op_sel_hi:[1,0]
	v_pk_mul_f32 v[234:235], v[226:227], s[48:49] op_sel_hi:[1,0]
	v_exp_f32_e32 v232, v232
	v_exp_f32_e32 v233, v233
	v_exp_f32_e32 v234, v234
	v_exp_f32_e32 v235, v235
	v_pk_add_f32 v[232:233], v[232:233], 1.0 op_sel_hi:[1,0]
	v_pk_add_f32 v[234:235], v[234:235], 1.0 op_sel_hi:[1,0]
	v_rcp_f32_e32 v232, v232
	v_rcp_f32_e32 v233, v233
	v_rcp_f32_e32 v234, v234
	v_rcp_f32_e32 v235, v235
	v_lshl_add_u64 v[220:221], v[220:221], 0, s[96:97]
	v_pk_mul_f32 v[224:225], v[224:225], v[232:233]
	v_pk_mul_f32 v[226:227], v[226:227], v[234:235]
	v_pk_mul_f32 v[224:225], v[224:225], v[228:229]
	v_pk_mul_f32 v[226:227], v[226:227], v[230:231]
	v_cvt_pk_bf16_f32 v168, v224, v225
	v_cvt_pk_bf16_f32 v169, v226, v227
	global_store_dwordx2 v[220:221], v[168:169], off offset:32
	v_pk_fma_f32 v[224:225], v[34:35], v[186:187], v[190:191]
	v_pk_fma_f32 v[226:227], v[36:37], v[188:189], v[192:193]
	v_pk_fma_f32 v[228:229], v[10:11], v[202:203], v[206:207]
	v_pk_fma_f32 v[230:231], v[12:13], v[204:205], v[208:209]
	v_fmac_f32_dpp v224, v34, v182 row_shr:1 row_mask:0xf bank_mask:0xf bound_ctrl:1
	v_fmac_f32_dpp v225, v35, v183 row_shr:1 row_mask:0xf bank_mask:0xf bound_ctrl:1
	v_fmac_f32_dpp v226, v36, v184 row_shr:1 row_mask:0xf bank_mask:0xf bound_ctrl:1
	v_fmac_f32_dpp v227, v37, v185 row_shr:1 row_mask:0xf bank_mask:0xf bound_ctrl:1
	v_fmac_f32_dpp v228, v10, v198 row_shr:1 row_mask:0xf bank_mask:0xf bound_ctrl:1
	v_fmac_f32_dpp v229, v11, v199 row_shr:1 row_mask:0xf bank_mask:0xf bound_ctrl:1
	v_fmac_f32_dpp v230, v12, v200 row_shr:1 row_mask:0xf bank_mask:0xf bound_ctrl:1
	v_fmac_f32_dpp v231, v13, v201 row_shr:1 row_mask:0xf bank_mask:0xf bound_ctrl:1
	v_fmac_f32_dpp v224, v34, v178 row_shr:2 row_mask:0xf bank_mask:0xf bound_ctrl:1
	v_fmac_f32_dpp v225, v35, v179 row_shr:2 row_mask:0xf bank_mask:0xf bound_ctrl:1
	v_fmac_f32_dpp v226, v36, v180 row_shr:2 row_mask:0xf bank_mask:0xf bound_ctrl:1
	v_fmac_f32_dpp v227, v37, v181 row_shr:2 row_mask:0xf bank_mask:0xf bound_ctrl:1
	v_fmac_f32_dpp v228, v10, v194 row_shr:2 row_mask:0xf bank_mask:0xf bound_ctrl:1
	v_fmac_f32_dpp v229, v11, v195 row_shr:2 row_mask:0xf bank_mask:0xf bound_ctrl:1
	v_fmac_f32_dpp v230, v12, v196 row_shr:2 row_mask:0xf bank_mask:0xf bound_ctrl:1
	v_fmac_f32_dpp v231, v13, v197 row_shr:2 row_mask:0xf bank_mask:0xf bound_ctrl:1
	v_fmac_f32_dpp v224, v50, v182 row_shl:15 row_mask:0xf bank_mask:0xf bound_ctrl:1
	v_fmac_f32_dpp v225, v51, v183 row_shl:15 row_mask:0xf bank_mask:0xf bound_ctrl:1
	v_fmac_f32_dpp v226, v52, v184 row_shl:15 row_mask:0xf bank_mask:0xf bound_ctrl:1
	v_fmac_f32_dpp v227, v53, v185 row_shl:15 row_mask:0xf bank_mask:0xf bound_ctrl:1
	v_fmac_f32_dpp v228, v22, v198 row_shl:15 row_mask:0xf bank_mask:0xf bound_ctrl:1
	v_fmac_f32_dpp v229, v23, v199 row_shl:15 row_mask:0xf bank_mask:0xf bound_ctrl:1
	v_fmac_f32_dpp v230, v24, v200 row_shl:15 row_mask:0xf bank_mask:0xf bound_ctrl:1
	v_fmac_f32_dpp v231, v25, v201 row_shl:15 row_mask:0xf bank_mask:0xf bound_ctrl:1
	v_fmac_f32_dpp v224, v50, v178 row_shl:14 row_mask:0xf bank_mask:0xf bound_ctrl:1
	v_fmac_f32_dpp v225, v51, v179 row_shl:14 row_mask:0xf bank_mask:0xf bound_ctrl:1
	v_fmac_f32_dpp v226, v52, v180 row_shl:14 row_mask:0xf bank_mask:0xf bound_ctrl:1
	v_fmac_f32_dpp v227, v53, v181 row_shl:14 row_mask:0xf bank_mask:0xf bound_ctrl:1
	v_fmac_f32_dpp v228, v22, v194 row_shl:14 row_mask:0xf bank_mask:0xf bound_ctrl:1
	v_fmac_f32_dpp v229, v23, v195 row_shl:14 row_mask:0xf bank_mask:0xf bound_ctrl:1
	v_fmac_f32_dpp v230, v24, v196 row_shl:14 row_mask:0xf bank_mask:0xf bound_ctrl:1
	v_fmac_f32_dpp v231, v25, v197 row_shl:14 row_mask:0xf bank_mask:0xf bound_ctrl:1
	v_pk_mul_f32 v[232:233], v[224:225], s[48:49] op_sel_hi:[1,0]
	v_pk_mul_f32 v[234:235], v[226:227], s[48:49] op_sel_hi:[1,0]
	v_exp_f32_e32 v232, v232
	v_exp_f32_e32 v233, v233
	v_exp_f32_e32 v234, v234
	v_exp_f32_e32 v235, v235
	v_pk_add_f32 v[232:233], v[232:233], 1.0 op_sel_hi:[1,0]
	v_pk_add_f32 v[234:235], v[234:235], 1.0 op_sel_hi:[1,0]
	v_rcp_f32_e32 v232, v232
	v_rcp_f32_e32 v233, v233
	v_rcp_f32_e32 v234, v234
	v_rcp_f32_e32 v235, v235
	v_lshl_add_u64 v[220:221], v[220:221], 0, s[96:97]
	v_pk_mul_f32 v[224:225], v[224:225], v[232:233]
	v_pk_mul_f32 v[226:227], v[226:227], v[234:235]
	v_pk_mul_f32 v[224:225], v[224:225], v[228:229]
	v_pk_mul_f32 v[226:227], v[226:227], v[230:231]
	v_cvt_pk_bf16_f32 v168, v224, v225
	v_cvt_pk_bf16_f32 v169, v226, v227
	global_store_dwordx2 v[220:221], v[168:169], off offset:32
	s_add_u32 s94, s26, s85
	s_addc_u32 s95, s27, 0
	v_lshl_add_u64 v[222:223], s[94:95], 0, v[216:217]
	v_lshl_add_u64 v[246:247], s[94:95], 0, v[218:219]
	s_and_saveexec_b64 s[46:47], s[6:7]
	global_store_dwordx4 v[222:223], v[18:21], off offset:64
	global_store_dwordx4 v[246:247], v[2:5], off offset:64
	s_or_b64 exec, exec, s[46:47]
	v_pk_fma_f32 v[224:225], v[18:19], v[186:187], v[190:191]
	v_pk_fma_f32 v[226:227], v[20:21], v[188:189], v[192:193]
	v_pk_fma_f32 v[228:229], v[2:3], v[202:203], v[206:207]
	v_pk_fma_f32 v[230:231], v[4:5], v[204:205], v[208:209]
	v_fmac_f32_dpp v224, v18, v182 row_shr:1 row_mask:0xf bank_mask:0xf bound_ctrl:1
	v_fmac_f32_dpp v225, v19, v183 row_shr:1 row_mask:0xf bank_mask:0xf bound_ctrl:1
	v_fmac_f32_dpp v226, v20, v184 row_shr:1 row_mask:0xf bank_mask:0xf bound_ctrl:1
	v_fmac_f32_dpp v227, v21, v185 row_shr:1 row_mask:0xf bank_mask:0xf bound_ctrl:1
	v_fmac_f32_dpp v228, v2, v198 row_shr:1 row_mask:0xf bank_mask:0xf bound_ctrl:1
	v_fmac_f32_dpp v229, v3, v199 row_shr:1 row_mask:0xf bank_mask:0xf bound_ctrl:1
	v_fmac_f32_dpp v230, v4, v200 row_shr:1 row_mask:0xf bank_mask:0xf bound_ctrl:1
	v_fmac_f32_dpp v231, v5, v201 row_shr:1 row_mask:0xf bank_mask:0xf bound_ctrl:1
	v_fmac_f32_dpp v224, v18, v178 row_shr:2 row_mask:0xf bank_mask:0xf bound_ctrl:1
	v_fmac_f32_dpp v225, v19, v179 row_shr:2 row_mask:0xf bank_mask:0xf bound_ctrl:1
	v_fmac_f32_dpp v226, v20, v180 row_shr:2 row_mask:0xf bank_mask:0xf bound_ctrl:1
	v_fmac_f32_dpp v227, v21, v181 row_shr:2 row_mask:0xf bank_mask:0xf bound_ctrl:1
	v_fmac_f32_dpp v228, v2, v194 row_shr:2 row_mask:0xf bank_mask:0xf bound_ctrl:1
	v_fmac_f32_dpp v229, v3, v195 row_shr:2 row_mask:0xf bank_mask:0xf bound_ctrl:1
	v_fmac_f32_dpp v230, v4, v196 row_shr:2 row_mask:0xf bank_mask:0xf bound_ctrl:1
	v_fmac_f32_dpp v231, v5, v197 row_shr:2 row_mask:0xf bank_mask:0xf bound_ctrl:1
	v_fmac_f32_dpp v224, v34, v182 row_shl:15 row_mask:0xf bank_mask:0xf bound_ctrl:1
	v_fmac_f32_dpp v225, v35, v183 row_shl:15 row_mask:0xf bank_mask:0xf bound_ctrl:1
	v_fmac_f32_dpp v226, v36, v184 row_shl:15 row_mask:0xf bank_mask:0xf bound_ctrl:1
	v_fmac_f32_dpp v227, v37, v185 row_shl:15 row_mask:0xf bank_mask:0xf bound_ctrl:1
	v_fmac_f32_dpp v228, v10, v198 row_shl:15 row_mask:0xf bank_mask:0xf bound_ctrl:1
	v_fmac_f32_dpp v229, v11, v199 row_shl:15 row_mask:0xf bank_mask:0xf bound_ctrl:1
	v_fmac_f32_dpp v230, v12, v200 row_shl:15 row_mask:0xf bank_mask:0xf bound_ctrl:1
	v_fmac_f32_dpp v231, v13, v201 row_shl:15 row_mask:0xf bank_mask:0xf bound_ctrl:1
	v_fmac_f32_dpp v224, v34, v178 row_shl:14 row_mask:0xf bank_mask:0xf bound_ctrl:1
	v_fmac_f32_dpp v225, v35, v179 row_shl:14 row_mask:0xf bank_mask:0xf bound_ctrl:1
	v_fmac_f32_dpp v226, v36, v180 row_shl:14 row_mask:0xf bank_mask:0xf bound_ctrl:1
	v_fmac_f32_dpp v227, v37, v181 row_shl:14 row_mask:0xf bank_mask:0xf bound_ctrl:1
	v_fmac_f32_dpp v228, v10, v194 row_shl:14 row_mask:0xf bank_mask:0xf bound_ctrl:1
	v_fmac_f32_dpp v229, v11, v195 row_shl:14 row_mask:0xf bank_mask:0xf bound_ctrl:1
	v_fmac_f32_dpp v230, v12, v196 row_shl:14 row_mask:0xf bank_mask:0xf bound_ctrl:1
	v_fmac_f32_dpp v231, v13, v197 row_shl:14 row_mask:0xf bank_mask:0xf bound_ctrl:1
	v_pk_mul_f32 v[232:233], v[224:225], s[48:49] op_sel_hi:[1,0]
	v_pk_mul_f32 v[234:235], v[226:227], s[48:49] op_sel_hi:[1,0]
	v_exp_f32_e32 v232, v232
	v_exp_f32_e32 v233, v233
	v_exp_f32_e32 v234, v234
	v_exp_f32_e32 v235, v235
	v_pk_add_f32 v[232:233], v[232:233], 1.0 op_sel_hi:[1,0]
	v_pk_add_f32 v[234:235], v[234:235], 1.0 op_sel_hi:[1,0]
	v_rcp_f32_e32 v232, v232
	v_rcp_f32_e32 v233, v233
	v_rcp_f32_e32 v234, v234
	v_rcp_f32_e32 v235, v235
	v_lshl_add_u64 v[220:221], v[220:221], 0, s[96:97]
	v_pk_mul_f32 v[224:225], v[224:225], v[232:233]
	v_pk_mul_f32 v[226:227], v[226:227], v[234:235]
	v_pk_mul_f32 v[224:225], v[224:225], v[228:229]
	v_pk_mul_f32 v[226:227], v[226:227], v[230:231]
	v_cvt_pk_bf16_f32 v168, v224, v225
	v_cvt_pk_bf16_f32 v169, v226, v227
	global_store_dwordx2 v[220:221], v[168:169], off offset:32
	s_branch .LBB0_1094

.LBB0_1296:
	v_add_u32_e32 v154, 0x18000, v173
	v_add_u32_e32 v155, 0x1c000, v173
	ds_read_b128 v[126:129], v175
	ds_read_b128 v[134:137], v175 offset:1024
	ds_read_b128 v[138:141], v175 offset:2048
	ds_read_b128 v[142:145], v175 offset:3072
	ds_read_b128 v[158:161], v176
	ds_read_b128 v[178:181], v176 offset:1024
	ds_read_b128 v[182:185], v176 offset:2048
	ds_read_b128 v[186:189], v176 offset:3072
	ds_read_b128 v[190:193], v176 offset:4096
	ds_read_b128 v[194:197], v176 offset:5120
	ds_read_b128 v[198:201], v176 offset:6144
	ds_read_b128 v[202:205], v176 offset:7168
	s_add_u32 s28, s28, 0x160080
	s_addc_u32 s29, s29, 0
	s_add_u32 s58, s30, 0x100
	s_addc_u32 s59, s31, 0
	s_mov_b32 s60, -2
	s_add_u32 s30, s28, 0xffea0080
	s_addc_u32 s31, s29, -1
	s_cmpk_eq_i32 s60, 0x54
	s_cselect_b32 s35, s7, s31
	s_cselect_b32 s34, s6, s30
	s_cselect_b32 s31, s9, s59
	s_cselect_b32 s30, s8, s58
	s_add_i32 m0, s43, 0xc000
	s_nop 0
	global_load_lds_dwordx4 v150, s[28:29]
	s_add_i32 m0, s43, 0xe000
	s_nop 0
	global_load_lds_dwordx4 v152, s[28:29]
	s_waitcnt vmcnt(10)
	s_barrier
	s_waitcnt lgkmcnt(0)
	s_setprio 1
	v_mfma_f32_16x16x32_bf16 v[130:133], v[126:129], v[158:161], 0
	ds_read_b128 v[206:209], v177
	v_mfma_f32_16x16x32_bf16 v[122:125], v[138:141], v[158:161], 0
	v_mfma_f32_16x16x32_bf16 v[118:121], v[126:129], v[182:185], 0
	v_mfma_f32_16x16x32_bf16 v[114:117], v[138:141], v[182:185], 0
	v_mfma_f32_16x16x32_bf16 v[102:105], v[126:129], v[190:193], 0
	ds_read_b128 v[210:213], v177 offset:1024
	v_mfma_f32_16x16x32_bf16 v[98:101], v[138:141], v[190:193], 0
	v_mfma_f32_16x16x32_bf16 v[86:89], v[126:129], v[198:201], 0
	v_mfma_f32_16x16x32_bf16 v[82:85], v[138:141], v[198:201], 0
	v_mfma_f32_16x16x32_bf16 v[130:133], v[134:137], v[178:181], v[130:133]
	ds_read_b128 v[214:217], v177 offset:2048
	v_mfma_f32_16x16x32_bf16 v[122:125], v[142:145], v[178:181], v[122:125]
	v_mfma_f32_16x16x32_bf16 v[118:121], v[134:137], v[186:189], v[118:121]
	v_mfma_f32_16x16x32_bf16 v[114:117], v[142:145], v[186:189], v[114:117]
	v_mfma_f32_16x16x32_bf16 v[102:105], v[134:137], v[194:197], v[102:105]
	ds_read_b128 v[218:221], v177 offset:3072
	v_mfma_f32_16x16x32_bf16 v[98:101], v[142:145], v[194:197], v[98:101]
	v_mfma_f32_16x16x32_bf16 v[86:89], v[134:137], v[202:205], v[86:89]
	v_mfma_f32_16x16x32_bf16 v[82:85], v[142:145], v[202:205], v[82:85]
	s_setprio 0
	s_barrier
	s_add_i32 s61, s51, s40
	s_add_u32 s96, s30, 0x80
	s_addc_u32 s97, s31, 0
	s_mov_b32 m0, s61
	s_nop 0
	global_load_lds_dwordx4 v146, s[30:31]
	s_add_i32 m0, s61, 0x2000
	s_nop 0
	global_load_lds_dwordx4 v148, s[30:31]
	s_waitcnt vmcnt(10)
	s_barrier
	s_waitcnt lgkmcnt(0)
	s_setprio 1
	v_mfma_f32_16x16x32_bf16 v[110:113], v[206:209], v[158:161], 0
	ds_read_b128 v[226:229], v176 offset:16384
	v_mfma_f32_16x16x32_bf16 v[106:109], v[214:217], v[158:161], 0
	v_mfma_f32_16x16x32_bf16 v[94:97], v[206:209], v[182:185], 0
	ds_read_b128 v[230:233], v176 offset:17408
	v_mfma_f32_16x16x32_bf16 v[90:93], v[214:217], v[182:185], 0
	v_mfma_f32_16x16x32_bf16 v[78:81], v[206:209], v[190:193], 0
	ds_read_b128 v[234:237], v176 offset:18432
	v_mfma_f32_16x16x32_bf16 v[74:77], v[214:217], v[190:193], 0
	v_mfma_f32_16x16x32_bf16 v[70:73], v[206:209], v[198:201], 0
	ds_read_b128 v[238:241], v176 offset:19456
	v_mfma_f32_16x16x32_bf16 v[66:69], v[214:217], v[198:201], 0
	v_mfma_f32_16x16x32_bf16 v[110:113], v[210:213], v[178:181], v[110:113]
	ds_read_b128 v[242:245], v176 offset:20480
	v_mfma_f32_16x16x32_bf16 v[106:109], v[218:221], v[178:181], v[106:109]
	v_mfma_f32_16x16x32_bf16 v[94:97], v[210:213], v[186:189], v[94:97]
	ds_read_b128 v[246:249], v176 offset:21504
	v_mfma_f32_16x16x32_bf16 v[90:93], v[218:221], v[186:189], v[90:93]
	v_mfma_f32_16x16x32_bf16 v[78:81], v[210:213], v[194:197], v[78:81]
	ds_read_b128 v[250:253], v176 offset:22528
	v_mfma_f32_16x16x32_bf16 v[74:77], v[218:221], v[194:197], v[74:77]
	v_mfma_f32_16x16x32_bf16 v[70:73], v[210:213], v[202:205], v[70:73]
	ds_read_b128 v[222:225], v176 offset:23552
	v_mfma_f32_16x16x32_bf16 v[66:69], v[218:221], v[202:205], v[66:69]
	s_setprio 0
	s_barrier
	s_mov_b32 m0, s43
	s_add_u32 s94, s34, 0x80
	s_addc_u32 s95, s35, 0
	global_load_lds_dwordx4 v146, s[34:35]
	s_mov_b32 m0, s44
	s_nop 0
	global_load_lds_dwordx4 v148, s[34:35]
	s_waitcnt vmcnt(8)
	s_barrier
	s_waitcnt lgkmcnt(0)
	s_setprio 1
	v_mfma_f32_16x16x32_bf16 v[62:65], v[126:129], v[226:229], 0
	ds_read_b128 v[158:161], v176 offset:32768
	v_mfma_f32_16x16x32_bf16 v[58:61], v[138:141], v[226:229], 0
	v_mfma_f32_16x16x32_bf16 v[54:57], v[126:129], v[234:237], 0
	ds_read_b128 v[178:181], v176 offset:33792
	v_mfma_f32_16x16x32_bf16 v[46:49], v[138:141], v[234:237], 0
	v_mfma_f32_16x16x32_bf16 v[38:41], v[126:129], v[242:245], 0
	ds_read_b128 v[182:185], v176 offset:34816
	v_mfma_f32_16x16x32_bf16 v[30:33], v[138:141], v[242:245], 0
	v_mfma_f32_16x16x32_bf16 v[22:25], v[126:129], v[250:253], 0
	ds_read_b128 v[186:189], v176 offset:35840
	v_mfma_f32_16x16x32_bf16 v[14:17], v[138:141], v[250:253], 0
	v_mfma_f32_16x16x32_bf16 v[62:65], v[134:137], v[230:233], v[62:65]
	ds_read_b128 v[190:193], v176 offset:36864
	v_mfma_f32_16x16x32_bf16 v[58:61], v[142:145], v[230:233], v[58:61]
	v_mfma_f32_16x16x32_bf16 v[54:57], v[134:137], v[238:241], v[54:57]
	ds_read_b128 v[194:197], v176 offset:37888
	v_mfma_f32_16x16x32_bf16 v[46:49], v[142:145], v[238:241], v[46:49]
	v_mfma_f32_16x16x32_bf16 v[38:41], v[134:137], v[246:249], v[38:41]
	ds_read_b128 v[198:201], v176 offset:38912
	v_mfma_f32_16x16x32_bf16 v[30:33], v[142:145], v[246:249], v[30:33]
	v_mfma_f32_16x16x32_bf16 v[22:25], v[134:137], v[222:225], v[22:25]
	ds_read_b128 v[202:205], v176 offset:39936
	v_mfma_f32_16x16x32_bf16 v[14:17], v[142:145], v[222:225], v[14:17]
	s_setprio 0
	s_barrier
	s_add_u32 s62, s30, 0x160000
	s_addc_u32 s63, s31, 0
	s_add_i32 s61, s52, s40
	s_mov_b32 m0, s61
	s_nop 0
	global_load_lds_dwordx4 v146, s[62:63]
	s_add_i32 m0, s61, 0x2000
	s_nop 0
	global_load_lds_dwordx4 v148, s[62:63]
	s_waitcnt vmcnt(10)
	s_barrier
	s_waitcnt lgkmcnt(0)
	s_setprio 1
	v_mfma_f32_16x16x32_bf16 v[50:53], v[206:209], v[226:229], 0
	ds_read_b128 v[126:129], v154
	v_mfma_f32_16x16x32_bf16 v[42:45], v[214:217], v[226:229], 0
	v_mfma_f32_16x16x32_bf16 v[34:37], v[206:209], v[234:237], 0
	v_mfma_f32_16x16x32_bf16 v[26:29], v[214:217], v[234:237], 0
	v_mfma_f32_16x16x32_bf16 v[18:21], v[206:209], v[242:245], 0
	ds_read_b128 v[134:137], v154 offset:1024
	v_mfma_f32_16x16x32_bf16 v[10:13], v[214:217], v[242:245], 0
	v_mfma_f32_16x16x32_bf16 v[6:9], v[206:209], v[250:253], 0
	v_mfma_f32_16x16x32_bf16 v[2:5], v[214:217], v[250:253], 0
	v_mfma_f32_16x16x32_bf16 v[50:53], v[210:213], v[230:233], v[50:53]
	ds_read_b128 v[138:141], v154 offset:2048
	v_mfma_f32_16x16x32_bf16 v[42:45], v[218:221], v[230:233], v[42:45]
	v_mfma_f32_16x16x32_bf16 v[34:37], v[210:213], v[238:241], v[34:37]
	v_mfma_f32_16x16x32_bf16 v[26:29], v[218:221], v[238:241], v[26:29]
	v_mfma_f32_16x16x32_bf16 v[18:21], v[210:213], v[246:249], v[18:21]
	ds_read_b128 v[142:145], v154 offset:3072
	v_mfma_f32_16x16x32_bf16 v[10:13], v[218:221], v[246:249], v[10:13]
	v_mfma_f32_16x16x32_bf16 v[6:9], v[210:213], v[222:225], v[6:9]
	v_mfma_f32_16x16x32_bf16 v[2:5], v[218:221], v[222:225], v[2:5]
	s_setprio 0
	s_barrier
	s_add_i32 s61, 0, 0x18000
	s_add_u32 s34, s34, 0x160000
	s_addc_u32 s35, s35, 0
	s_mov_b32 m0, s45
	s_nop 0
	global_load_lds_dwordx4 v146, s[34:35]
	s_mov_b32 m0, s46
	s_nop 0
	global_load_lds_dwordx4 v148, s[34:35]
	s_waitcnt vmcnt(10)
	s_barrier
	s_waitcnt lgkmcnt(0)
	s_setprio 1
	v_mfma_f32_16x16x32_bf16 v[130:133], v[126:129], v[158:161], v[130:133]
	ds_read_b128 v[206:209], v155
	v_mfma_f32_16x16x32_bf16 v[122:125], v[138:141], v[158:161], v[122:125]
	v_mfma_f32_16x16x32_bf16 v[118:121], v[126:129], v[182:185], v[118:121]
	v_mfma_f32_16x16x32_bf16 v[114:117], v[138:141], v[182:185], v[114:117]
	v_mfma_f32_16x16x32_bf16 v[102:105], v[126:129], v[190:193], v[102:105]
	ds_read_b128 v[210:213], v155 offset:1024
	v_mfma_f32_16x16x32_bf16 v[98:101], v[138:141], v[190:193], v[98:101]
	v_mfma_f32_16x16x32_bf16 v[86:89], v[126:129], v[198:201], v[86:89]
	v_mfma_f32_16x16x32_bf16 v[82:85], v[138:141], v[198:201], v[82:85]
	v_mfma_f32_16x16x32_bf16 v[130:133], v[134:137], v[178:181], v[130:133]
	ds_read_b128 v[214:217], v155 offset:2048
	v_mfma_f32_16x16x32_bf16 v[122:125], v[142:145], v[178:181], v[122:125]
	v_mfma_f32_16x16x32_bf16 v[118:121], v[134:137], v[186:189], v[118:121]
	v_mfma_f32_16x16x32_bf16 v[114:117], v[142:145], v[186:189], v[114:117]
	v_mfma_f32_16x16x32_bf16 v[102:105], v[134:137], v[194:197], v[102:105]
	ds_read_b128 v[218:221], v155 offset:3072
	v_mfma_f32_16x16x32_bf16 v[98:101], v[142:145], v[194:197], v[98:101]
	v_mfma_f32_16x16x32_bf16 v[86:89], v[134:137], v[202:205], v[86:89]
	v_mfma_f32_16x16x32_bf16 v[82:85], v[142:145], v[202:205], v[82:85]
	s_setprio 0
	s_barrier
	s_add_i32 s84, 0, 0x1c000
	s_add_i32 s85, s61, s40
	s_mov_b32 m0, s85
	s_nop 0
	global_load_lds_dwordx4 v146, s[96:97]
	s_add_i32 m0, s85, 0x2000
	s_nop 0
	global_load_lds_dwordx4 v148, s[96:97]
	s_waitcnt vmcnt(10)
	s_barrier
	s_waitcnt lgkmcnt(0)
	s_setprio 1
	v_mfma_f32_16x16x32_bf16 v[110:113], v[206:209], v[158:161], v[110:113]
	ds_read_b128 v[226:229], v176 offset:49152
	v_mfma_f32_16x16x32_bf16 v[106:109], v[214:217], v[158:161], v[106:109]
	v_mfma_f32_16x16x32_bf16 v[94:97], v[206:209], v[182:185], v[94:97]
	ds_read_b128 v[230:233], v176 offset:50176
	v_mfma_f32_16x16x32_bf16 v[90:93], v[214:217], v[182:185], v[90:93]
	v_mfma_f32_16x16x32_bf16 v[78:81], v[206:209], v[190:193], v[78:81]
	ds_read_b128 v[234:237], v176 offset:51200
	v_mfma_f32_16x16x32_bf16 v[74:77], v[214:217], v[190:193], v[74:77]
	v_mfma_f32_16x16x32_bf16 v[70:73], v[206:209], v[198:201], v[70:73]
	ds_read_b128 v[238:241], v176 offset:52224
	v_mfma_f32_16x16x32_bf16 v[66:69], v[214:217], v[198:201], v[66:69]
	v_mfma_f32_16x16x32_bf16 v[110:113], v[210:213], v[178:181], v[110:113]
	ds_read_b128 v[242:245], v176 offset:53248
	v_mfma_f32_16x16x32_bf16 v[106:109], v[218:221], v[178:181], v[106:109]
	v_mfma_f32_16x16x32_bf16 v[94:97], v[210:213], v[186:189], v[94:97]
	ds_read_b128 v[246:249], v176 offset:54272
	v_mfma_f32_16x16x32_bf16 v[90:93], v[218:221], v[186:189], v[90:93]
	v_mfma_f32_16x16x32_bf16 v[78:81], v[210:213], v[194:197], v[78:81]
	ds_read_b128 v[250:253], v176 offset:55296
	v_mfma_f32_16x16x32_bf16 v[74:77], v[218:221], v[194:197], v[74:77]
	v_mfma_f32_16x16x32_bf16 v[70:73], v[210:213], v[202:205], v[70:73]
	ds_read_b128 v[222:225], v176 offset:56320
	v_mfma_f32_16x16x32_bf16 v[66:69], v[218:221], v[202:205], v[66:69]
	s_setprio 0
	s_barrier
	s_mov_b32 m0, s48
	s_nop 0
	global_load_lds_dwordx4 v146, s[94:95]
	s_mov_b32 m0, s49
	s_nop 0
	global_load_lds_dwordx4 v148, s[94:95]
	s_waitcnt vmcnt(8)
	s_barrier
	s_waitcnt lgkmcnt(0)
	s_setprio 1
	v_mfma_f32_16x16x32_bf16 v[62:65], v[126:129], v[226:229], v[62:65]
	ds_read_b128 v[158:161], v176
	v_mfma_f32_16x16x32_bf16 v[58:61], v[138:141], v[226:229], v[58:61]
	v_mfma_f32_16x16x32_bf16 v[54:57], v[126:129], v[234:237], v[54:57]
	ds_read_b128 v[178:181], v176 offset:1024
	v_mfma_f32_16x16x32_bf16 v[46:49], v[138:141], v[234:237], v[46:49]
	v_mfma_f32_16x16x32_bf16 v[38:41], v[126:129], v[242:245], v[38:41]
	ds_read_b128 v[182:185], v176 offset:2048
	v_mfma_f32_16x16x32_bf16 v[30:33], v[138:141], v[242:245], v[30:33]
	v_mfma_f32_16x16x32_bf16 v[22:25], v[126:129], v[250:253], v[22:25]
	ds_read_b128 v[186:189], v176 offset:3072
	v_mfma_f32_16x16x32_bf16 v[14:17], v[138:141], v[250:253], v[14:17]
	v_mfma_f32_16x16x32_bf16 v[62:65], v[134:137], v[230:233], v[62:65]
	ds_read_b128 v[190:193], v176 offset:4096
	v_mfma_f32_16x16x32_bf16 v[58:61], v[142:145], v[230:233], v[58:61]
	v_mfma_f32_16x16x32_bf16 v[54:57], v[134:137], v[238:241], v[54:57]
	ds_read_b128 v[194:197], v176 offset:5120
	v_mfma_f32_16x16x32_bf16 v[46:49], v[142:145], v[238:241], v[46:49]
	v_mfma_f32_16x16x32_bf16 v[38:41], v[134:137], v[246:249], v[38:41]
	ds_read_b128 v[198:201], v176 offset:6144
	v_mfma_f32_16x16x32_bf16 v[30:33], v[142:145], v[246:249], v[30:33]
	v_mfma_f32_16x16x32_bf16 v[22:25], v[134:137], v[222:225], v[22:25]
	ds_read_b128 v[202:205], v176 offset:7168
	v_mfma_f32_16x16x32_bf16 v[14:17], v[142:145], v[222:225], v[14:17]
	s_setprio 0
	s_barrier
	s_add_u32 s30, s30, 0x160080
	s_addc_u32 s31, s31, 0
	s_add_i32 s84, s84, s40
	s_mov_b32 m0, s84
	s_nop 0
	global_load_lds_dwordx4 v146, s[30:31]
	s_add_i32 m0, s84, 0x2000
	s_nop 0
	global_load_lds_dwordx4 v148, s[30:31]
	s_waitcnt vmcnt(10)
	s_barrier
	s_waitcnt lgkmcnt(0)
	s_setprio 1
	v_mfma_f32_16x16x32_bf16 v[50:53], v[206:209], v[226:229], v[50:53]
	ds_read_b128 v[126:129], v175
	v_mfma_f32_16x16x32_bf16 v[42:45], v[214:217], v[226:229], v[42:45]
	v_mfma_f32_16x16x32_bf16 v[34:37], v[206:209], v[234:237], v[34:37]
	v_mfma_f32_16x16x32_bf16 v[26:29], v[214:217], v[234:237], v[26:29]
	v_mfma_f32_16x16x32_bf16 v[18:21], v[206:209], v[242:245], v[18:21]
	ds_read_b128 v[134:137], v175 offset:1024
	v_mfma_f32_16x16x32_bf16 v[10:13], v[214:217], v[242:245], v[10:13]
	v_mfma_f32_16x16x32_bf16 v[6:9], v[206:209], v[250:253], v[6:9]
	v_mfma_f32_16x16x32_bf16 v[2:5], v[214:217], v[250:253], v[2:5]
	v_mfma_f32_16x16x32_bf16 v[50:53], v[210:213], v[230:233], v[50:53]
	ds_read_b128 v[138:141], v175 offset:2048
	v_mfma_f32_16x16x32_bf16 v[42:45], v[218:221], v[230:233], v[42:45]
	v_mfma_f32_16x16x32_bf16 v[34:37], v[210:213], v[238:241], v[34:37]
	v_mfma_f32_16x16x32_bf16 v[26:29], v[218:221], v[238:241], v[26:29]
	v_mfma_f32_16x16x32_bf16 v[18:21], v[210:213], v[246:249], v[18:21]
	ds_read_b128 v[142:145], v175 offset:3072
	v_mfma_f32_16x16x32_bf16 v[10:13], v[218:221], v[246:249], v[10:13]
	v_mfma_f32_16x16x32_bf16 v[6:9], v[210:213], v[222:225], v[6:9]
	v_mfma_f32_16x16x32_bf16 v[2:5], v[218:221], v[222:225], v[2:5]
	s_setprio 0
	s_add_i32 s60, s60, 2
	s_add_u32 s28, s28, 0x100
	s_addc_u32 s29, s29, 0
	s_add_u32 s58, s58, 0x100
	s_addc_u32 s59, s59, 0
	s_cmpk_gt_u32 s60, 0x55
	s_barrier
	s_cbranch_scc0 .LBB0_1297
	s_branch .Lp10_loop_exit
